# GEMM: next unit's first A-half DMA issued before the epilogue stores; third K-loop wait relaxed in first iteration too
# baseline (speedup 1.0000x reference)
.LBB0_43:
	s_add_u32 s22, s20, 0xfffc0080
	s_addc_u32 s23, s21, -1
	s_add_i32 s55, 0, 0x10000
	s_cmp_eq_u32 s49, 12
	s_cselect_b32 s25, s13, s23
	s_cselect_b32 s24, s45, s22
	v_add_u32_e32 v148, s55, v162
	s_cselect_b32 s23, s11, s48
	s_cselect_b32 s22, s46, s47
	s_add_i32 s58, 0, 0x14000
	ds_read_b128 v[140:143], v148
	ds_read_b128 v[144:147], v148 offset:1024
	ds_read_b128 v[154:157], v148 offset:2048
	ds_read_b128 v[166:169], v148 offset:3072
	v_add_u32_e32 v148, s58, v162
	ds_read_b128 v[170:173], v148
	ds_read_b128 v[174:177], v148 offset:1024
	ds_read_b128 v[178:181], v148 offset:2048
	ds_read_b128 v[182:185], v148 offset:3072
	v_lshl_add_u64 v[148:149], s[20:21], 0, v[138:139]
	s_add_i32 m0, s19, 0xc000
	ds_read_b128 v[186:189], v164
	ds_read_b128 v[190:193], v164 offset:1024
	ds_read_b128 v[194:197], v164 offset:2048
	ds_read_b128 v[198:201], v164 offset:3072
	ds_read_b128 v[202:205], v164 offset:4096
	ds_read_b128 v[206:209], v164 offset:5120
	ds_read_b128 v[210:213], v164 offset:6144
	ds_read_b128 v[222:225], v164 offset:7168
	s_cmp_lg_u32 s98, 0
	s_cbranch_scc1 .Lgc_skip_ff1
	global_load_lds_dwordx4 v[148:149], off
	v_lshl_add_u64 v[148:149], s[20:21], 0, v[136:137]
	s_add_i32 m0, s19, 0xe000
	s_nop 0
	global_load_lds_dwordx4 v[148:149], off
.Lgc_skip_ff1:
	s_cmp_lg_u32 s98, 0
	s_cbranch_scc1 .Lrelax_ff1_w1
	s_waitcnt vmcnt(8)

.Lback_ff1_w2:
	s_waitcnt lgkmcnt(0)
	s_barrier
	s_setprio 1
	s_waitcnt lgkmcnt(0)
	v_mfma_f32_16x16x32_bf16 v[62:65], v[140:143], v[186:189], v[62:65]
	v_mfma_f32_16x16x32_bf16 v[58:61], v[154:157], v[186:189], v[58:61]
	v_mfma_f32_16x16x32_bf16 v[46:49], v[140:143], v[194:197], v[46:49]
	v_mfma_f32_16x16x32_bf16 v[42:45], v[154:157], v[194:197], v[42:45]
	v_mfma_f32_16x16x32_bf16 v[30:33], v[140:143], v[202:205], v[30:33]
	v_mfma_f32_16x16x32_bf16 v[26:29], v[154:157], v[202:205], v[26:29]
	v_mfma_f32_16x16x32_bf16 v[14:17], v[140:143], v[210:213], v[14:17]
	v_mfma_f32_16x16x32_bf16 v[10:13], v[154:157], v[210:213], v[10:13]
	v_mfma_f32_16x16x32_bf16 v[62:65], v[144:147], v[190:193], v[62:65]
	v_mfma_f32_16x16x32_bf16 v[58:61], v[166:169], v[190:193], v[58:61]
	v_mfma_f32_16x16x32_bf16 v[46:49], v[144:147], v[198:201], v[46:49]
	v_mfma_f32_16x16x32_bf16 v[42:45], v[166:169], v[198:201], v[42:45]
	v_mfma_f32_16x16x32_bf16 v[30:33], v[144:147], v[206:209], v[30:33]
	v_mfma_f32_16x16x32_bf16 v[26:29], v[166:169], v[206:209], v[26:29]
	v_mfma_f32_16x16x32_bf16 v[14:17], v[144:147], v[222:225], v[14:17]
	v_mfma_f32_16x16x32_bf16 v[10:13], v[166:169], v[222:225], v[10:13]
	s_setprio 0
	s_setprio 1
	v_mfma_f32_16x16x32_bf16 v[54:57], v[170:173], v[186:189], v[54:57]
	v_mfma_f32_16x16x32_bf16 v[50:53], v[178:181], v[186:189], v[50:53]
	v_mfma_f32_16x16x32_bf16 v[38:41], v[170:173], v[194:197], v[38:41]
	v_mfma_f32_16x16x32_bf16 v[34:37], v[178:181], v[194:197], v[34:37]
	v_mfma_f32_16x16x32_bf16 v[22:25], v[170:173], v[202:205], v[22:25]
	v_mfma_f32_16x16x32_bf16 v[18:21], v[178:181], v[202:205], v[18:21]
	v_mfma_f32_16x16x32_bf16 v[6:9], v[170:173], v[210:213], v[6:9]
	v_mfma_f32_16x16x32_bf16 v[2:5], v[178:181], v[210:213], v[2:5]
	v_mfma_f32_16x16x32_bf16 v[54:57], v[174:177], v[190:193], v[54:57]
	v_mfma_f32_16x16x32_bf16 v[50:53], v[182:185], v[190:193], v[50:53]
	v_mfma_f32_16x16x32_bf16 v[38:41], v[174:177], v[198:201], v[38:41]
	v_mfma_f32_16x16x32_bf16 v[34:37], v[182:185], v[198:201], v[34:37]
	v_mfma_f32_16x16x32_bf16 v[22:25], v[174:177], v[206:209], v[22:25]
	v_mfma_f32_16x16x32_bf16 v[18:21], v[182:185], v[206:209], v[18:21]
	v_mfma_f32_16x16x32_bf16 v[6:9], v[174:177], v[222:225], v[6:9]
	v_mfma_f32_16x16x32_bf16 v[2:5], v[182:185], v[222:225], v[2:5]
	s_setprio 0
	s_barrier
	s_add_i32 s55, 0, 0x18000
	v_add_u32_e32 v165, s55, v162
	s_add_i32 s56, 0, 0x1c000
	ds_read_b128 v[140:143], v165
	ds_read_b128 v[144:147], v165 offset:1024
	ds_read_b128 v[154:157], v165 offset:2048
	ds_read_b128 v[166:169], v165 offset:3072
	v_add_u32_e32 v165, s56, v162
	ds_read_b128 v[170:173], v165
	ds_read_b128 v[174:177], v165 offset:1024
	ds_read_b128 v[178:181], v165 offset:2048
	ds_read_b128 v[182:185], v165 offset:3072
	s_add_u32 s24, s24, 0x40000
	s_addc_u32 s25, s25, 0
	s_mov_b32 m0, s38
	v_lshl_add_u64 v[232:233], s[24:25], 0, v[130:131]
	ds_read_b128 v[186:189], v164 offset:32768
	ds_read_b128 v[190:193], v164 offset:33792
	ds_read_b128 v[194:197], v164 offset:34816
	ds_read_b128 v[198:201], v164 offset:35840
	ds_read_b128 v[202:205], v164 offset:36864
	ds_read_b128 v[206:209], v164 offset:37888
	ds_read_b128 v[210:213], v164 offset:38912
	ds_read_b128 v[222:225], v164 offset:39936
	global_load_lds_dwordx4 v[232:233], off
	v_lshl_add_u64 v[232:233], s[24:25], 0, v[132:133]
	s_mov_b32 m0, s39
	s_nop 0
	global_load_lds_dwordx4 v[232:233], off
	s_cmp_lg_u32 s98, 0
	s_cbranch_scc1 .Lrelax_ff1_w3
	s_waitcnt vmcnt(8)
.Lback_ff1_w3:
	s_waitcnt lgkmcnt(0)
	s_barrier
	s_setprio 1
	s_waitcnt lgkmcnt(0)
	v_mfma_f32_16x16x32_bf16 v[126:129], v[140:143], v[186:189], v[126:129]
	v_mfma_f32_16x16x32_bf16 v[122:125], v[154:157], v[186:189], v[122:125]
	v_mfma_f32_16x16x32_bf16 v[110:113], v[140:143], v[194:197], v[110:113]
	v_mfma_f32_16x16x32_bf16 v[106:109], v[154:157], v[194:197], v[106:109]
	v_mfma_f32_16x16x32_bf16 v[94:97], v[140:143], v[202:205], v[94:97]
	v_mfma_f32_16x16x32_bf16 v[90:93], v[154:157], v[202:205], v[90:93]
	v_mfma_f32_16x16x32_bf16 v[78:81], v[140:143], v[210:213], v[78:81]
	v_mfma_f32_16x16x32_bf16 v[74:77], v[154:157], v[210:213], v[74:77]
	v_mfma_f32_16x16x32_bf16 v[126:129], v[144:147], v[190:193], v[126:129]
	v_mfma_f32_16x16x32_bf16 v[122:125], v[166:169], v[190:193], v[122:125]
	v_mfma_f32_16x16x32_bf16 v[110:113], v[144:147], v[198:201], v[110:113]
	v_mfma_f32_16x16x32_bf16 v[106:109], v[166:169], v[198:201], v[106:109]
	v_mfma_f32_16x16x32_bf16 v[94:97], v[144:147], v[206:209], v[94:97]
	v_mfma_f32_16x16x32_bf16 v[90:93], v[166:169], v[206:209], v[90:93]
	v_mfma_f32_16x16x32_bf16 v[78:81], v[144:147], v[222:225], v[78:81]
	v_mfma_f32_16x16x32_bf16 v[74:77], v[166:169], v[222:225], v[74:77]
	s_setprio 0
	s_setprio 1
	v_mfma_f32_16x16x32_bf16 v[118:121], v[170:173], v[186:189], v[118:121]
	v_mfma_f32_16x16x32_bf16 v[114:117], v[178:181], v[186:189], v[114:117]
	v_mfma_f32_16x16x32_bf16 v[102:105], v[170:173], v[194:197], v[102:105]
	v_mfma_f32_16x16x32_bf16 v[98:101], v[178:181], v[194:197], v[98:101]
	v_mfma_f32_16x16x32_bf16 v[86:89], v[170:173], v[202:205], v[86:89]
	v_mfma_f32_16x16x32_bf16 v[82:85], v[178:181], v[202:205], v[82:85]
	v_mfma_f32_16x16x32_bf16 v[70:73], v[170:173], v[210:213], v[70:73]
	v_mfma_f32_16x16x32_bf16 v[66:69], v[178:181], v[210:213], v[66:69]
	v_mfma_f32_16x16x32_bf16 v[118:121], v[174:177], v[190:193], v[118:121]
	v_mfma_f32_16x16x32_bf16 v[114:117], v[182:185], v[190:193], v[114:117]
	v_mfma_f32_16x16x32_bf16 v[102:105], v[174:177], v[198:201], v[102:105]
	v_mfma_f32_16x16x32_bf16 v[98:101], v[182:185], v[198:201], v[98:101]
	v_mfma_f32_16x16x32_bf16 v[86:89], v[174:177], v[206:209], v[86:89]
	v_mfma_f32_16x16x32_bf16 v[82:85], v[182:185], v[206:209], v[82:85]
	v_mfma_f32_16x16x32_bf16 v[70:73], v[174:177], v[222:225], v[70:73]
	v_mfma_f32_16x16x32_bf16 v[66:69], v[182:185], v[222:225], v[66:69]
	s_setprio 0
	s_barrier
	s_add_i32 s24, s55, s31
	v_lshl_add_u64 v[148:149], v[148:149], 0, s[96:97]
	s_mov_b32 m0, s24
	ds_read_b128 v[186:189], v164 offset:49152
	ds_read_b128 v[190:193], v164 offset:50176
	ds_read_b128 v[194:197], v164 offset:51200
	ds_read_b128 v[198:201], v164 offset:52224
	ds_read_b128 v[202:205], v164 offset:53248
	ds_read_b128 v[206:209], v164 offset:54272
	ds_read_b128 v[210:213], v164 offset:55296
	ds_read_b128 v[222:225], v164 offset:56320
	global_load_lds_dwordx4 v[148:149], off
	s_add_i32 m0, s24, 0x2000
	s_add_u32 s22, s22, 0x40080
	v_lshl_add_u64 v[148:149], v[226:227], 0, s[96:97]
	s_addc_u32 s23, s23, 0
	s_add_i32 s24, s56, s31
	global_load_lds_dwordx4 v[148:149], off
	v_lshl_add_u64 v[148:149], s[22:23], 0, v[0:1]
	s_mov_b32 m0, s24
	s_nop 0
	global_load_lds_dwordx4 v[148:149], off
	v_lshl_add_u64 v[148:149], s[22:23], 0, v[134:135]
	s_add_i32 m0, s24, 0x2000
	s_nop 0
	global_load_lds_dwordx4 v[148:149], off
	v_lshl_add_u64 v[148:149], v[228:229], 0, s[96:97]
	s_mov_b32 m0, s40
	s_nop 0
	global_load_lds_dwordx4 v[148:149], off
	v_lshl_add_u64 v[148:149], v[230:231], 0, s[96:97]
	s_mov_b32 m0, s41
	s_nop 0
	global_load_lds_dwordx4 v[148:149], off
	s_waitcnt vmcnt(8)
	s_waitcnt lgkmcnt(0)
	s_barrier
	s_setprio 1
	s_waitcnt lgkmcnt(0)
	v_mfma_f32_16x16x32_bf16 v[62:65], v[140:143], v[186:189], v[62:65]
	v_mfma_f32_16x16x32_bf16 v[58:61], v[154:157], v[186:189], v[58:61]
	v_mfma_f32_16x16x32_bf16 v[46:49], v[140:143], v[194:197], v[46:49]
	v_mfma_f32_16x16x32_bf16 v[42:45], v[154:157], v[194:197], v[42:45]
	v_mfma_f32_16x16x32_bf16 v[30:33], v[140:143], v[202:205], v[30:33]
	v_mfma_f32_16x16x32_bf16 v[26:29], v[154:157], v[202:205], v[26:29]
	v_mfma_f32_16x16x32_bf16 v[14:17], v[140:143], v[210:213], v[14:17]
	v_mfma_f32_16x16x32_bf16 v[10:13], v[154:157], v[210:213], v[10:13]
	v_mfma_f32_16x16x32_bf16 v[62:65], v[144:147], v[190:193], v[62:65]
	v_mfma_f32_16x16x32_bf16 v[58:61], v[166:169], v[190:193], v[58:61]
	v_mfma_f32_16x16x32_bf16 v[46:49], v[144:147], v[198:201], v[46:49]
	v_mfma_f32_16x16x32_bf16 v[42:45], v[166:169], v[198:201], v[42:45]
	v_mfma_f32_16x16x32_bf16 v[30:33], v[144:147], v[206:209], v[30:33]
	v_mfma_f32_16x16x32_bf16 v[26:29], v[166:169], v[206:209], v[26:29]
	v_mfma_f32_16x16x32_bf16 v[14:17], v[144:147], v[222:225], v[14:17]
	v_mfma_f32_16x16x32_bf16 v[10:13], v[166:169], v[222:225], v[10:13]
	s_setprio 0
	s_setprio 1
	v_mfma_f32_16x16x32_bf16 v[54:57], v[170:173], v[186:189], v[54:57]
	v_mfma_f32_16x16x32_bf16 v[50:53], v[178:181], v[186:189], v[50:53]
	v_mfma_f32_16x16x32_bf16 v[38:41], v[170:173], v[194:197], v[38:41]
	v_mfma_f32_16x16x32_bf16 v[34:37], v[178:181], v[194:197], v[34:37]
	v_mfma_f32_16x16x32_bf16 v[22:25], v[170:173], v[202:205], v[22:25]
	v_mfma_f32_16x16x32_bf16 v[18:21], v[178:181], v[202:205], v[18:21]
	v_mfma_f32_16x16x32_bf16 v[6:9], v[170:173], v[210:213], v[6:9]
	v_mfma_f32_16x16x32_bf16 v[2:5], v[178:181], v[210:213], v[2:5]
	v_mfma_f32_16x16x32_bf16 v[54:57], v[174:177], v[190:193], v[54:57]
	v_mfma_f32_16x16x32_bf16 v[50:53], v[182:185], v[190:193], v[50:53]
	v_mfma_f32_16x16x32_bf16 v[38:41], v[174:177], v[198:201], v[38:41]
	v_mfma_f32_16x16x32_bf16 v[34:37], v[182:185], v[198:201], v[34:37]
	v_mfma_f32_16x16x32_bf16 v[22:25], v[174:177], v[206:209], v[22:25]
	v_mfma_f32_16x16x32_bf16 v[18:21], v[182:185], v[206:209], v[18:21]
	v_mfma_f32_16x16x32_bf16 v[6:9], v[174:177], v[222:225], v[6:9]
	v_mfma_f32_16x16x32_bf16 v[2:5], v[182:185], v[222:225], v[2:5]
	s_setprio 0
	s_barrier
	s_add_i32 s49, s49, 2
	s_add_u32 s47, s47, 0x100
	s_addc_u32 s48, s48, 0
	s_add_u32 s20, s20, 0x100
	s_addc_u32 s21, s21, 0
	s_cmp_gt_u32 s49, 13
	s_cbranch_scc0 .LBB0_43
	s_add_u32 s20, s45, 0x40080
	s_addc_u32 s21, s13, 0
	s_and_b64 vcc, exec, s[8:9]
	s_movk_i32 s46, 0xd000
	s_movk_i32 s47, 0xec00
	s_cbranch_vccz .LBB0_46
	s_barrier
.LBB0_46:
	v_lshl_add_u64 v[148:149], s[20:21], 0, v[138:139]
	s_add_i32 m0, s19, 0xc000
	s_nop 0
	global_load_lds_dwordx4 v[148:149], off
	v_lshl_add_u64 v[148:149], s[20:21], 0, v[136:137]
	s_add_i32 m0, s19, 0xe000
	s_nop 0
	global_load_lds_dwordx4 v[148:149], off
	v_lshl_add_u32 v144, s18, 8, v159
	v_lshl_or_b32 v140, s44, 8, v163
	v_ashrrev_i32_e32 v141, 31, v140
	v_ashrrev_i32_e32 v145, 31, v144
	v_pk_add_f32 v[128:129], v[128:129], 0 op_sel_hi:[1,0]
	v_pk_add_f32 v[126:127], v[126:127], 0 op_sel_hi:[1,0]
	v_pk_add_f32 v[124:125], v[124:125], 0 op_sel_hi:[1,0]
	v_pk_add_f32 v[122:123], v[122:123], 0 op_sel_hi:[1,0]
	v_lshl_add_u64 v[142:143], v[140:141], 1, s[6:7]
	v_lshlrev_b64 v[140:141], 13, v[144:145]
	v_max_f32_e32 v127, 0, v127
	v_max_f32_e32 v126, 0, v126
	v_max_f32_e32 v129, 0, v129
	v_max_f32_e32 v128, 0, v128
	v_max_f32_e32 v123, 0, v123
	v_max_f32_e32 v122, 0, v122
	v_max_f32_e32 v125, 0, v125
	v_max_f32_e32 v124, 0, v124
	v_pk_add_f32 v[118:119], v[118:119], 0 op_sel_hi:[1,0]
	v_pk_add_f32 v[116:117], v[116:117], 0 op_sel_hi:[1,0]
	v_pk_add_f32 v[114:115], v[114:115], 0 op_sel_hi:[1,0]
	v_lshl_add_u64 v[140:141], v[142:143], 0, v[140:141]
	v_pk_mul_f32 v[128:129], v[128:129], v[128:129]
	v_pk_mul_f32 v[126:127], v[126:127], v[126:127]
	v_pk_mul_f32 v[146:147], v[124:125], v[124:125]
	v_pk_mul_f32 v[124:125], v[122:123], v[122:123]
	v_cvt_pk_bf16_f32 v122, v126, v127
	v_cvt_pk_bf16_f32 v123, v128, v129
	v_pk_add_f32 v[120:121], v[120:121], 0 op_sel_hi:[1,0]
	v_max_f32_e32 v119, 0, v119
	v_max_f32_e32 v118, 0, v118
	v_max_f32_e32 v115, 0, v115
	v_max_f32_e32 v114, 0, v114
	v_max_f32_e32 v117, 0, v117
	v_max_f32_e32 v116, 0, v116
	v_cvt_pk_bf16_f32 v124, v124, v125
	v_cvt_pk_bf16_f32 v125, v146, v147
	global_store_dwordx4 v[140:141], v[122:125], off nt
	v_max_f32_e32 v121, 0, v121
	v_max_f32_e32 v120, 0, v120
	v_pk_mul_f32 v[118:119], v[118:119], v[118:119]
	v_pk_mul_f32 v[122:123], v[116:117], v[116:117]
	v_pk_mul_f32 v[116:117], v[114:115], v[114:115]
	v_cvt_pk_bf16_f32 v114, v118, v119
	v_pk_mul_f32 v[120:121], v[120:121], v[120:121]
	v_pk_add_f32 v[112:113], v[112:113], 0 op_sel_hi:[1,0]
	v_cvt_pk_bf16_f32 v115, v120, v121
	v_cvt_pk_bf16_f32 v116, v116, v117
	v_cvt_pk_bf16_f32 v117, v122, v123
	global_store_dwordx4 v[140:141], v[114:117], off offset:256 nt
	v_pk_add_f32 v[110:111], v[110:111], 0 op_sel_hi:[1,0]
	v_pk_add_f32 v[108:109], v[108:109], 0 op_sel_hi:[1,0]
	v_or_b32_e32 v114, 16, v144
	v_ashrrev_i32_e32 v115, 31, v114
	v_pk_add_f32 v[106:107], v[106:107], 0 op_sel_hi:[1,0]
	v_lshlrev_b64 v[114:115], 13, v[114:115]
	v_max_f32_e32 v111, 0, v111
	v_max_f32_e32 v110, 0, v110
	v_max_f32_e32 v113, 0, v113
	v_max_f32_e32 v112, 0, v112
	v_max_f32_e32 v107, 0, v107
	v_max_f32_e32 v106, 0, v106
	v_max_f32_e32 v109, 0, v109
	v_max_f32_e32 v108, 0, v108
	v_pk_add_f32 v[102:103], v[102:103], 0 op_sel_hi:[1,0]
	v_pk_add_f32 v[100:101], v[100:101], 0 op_sel_hi:[1,0]
	v_pk_add_f32 v[98:99], v[98:99], 0 op_sel_hi:[1,0]
	v_lshl_add_u64 v[114:115], v[142:143], 0, v[114:115]
	v_pk_mul_f32 v[112:113], v[112:113], v[112:113]
	v_pk_mul_f32 v[110:111], v[110:111], v[110:111]
	v_pk_mul_f32 v[116:117], v[108:109], v[108:109]
	v_pk_mul_f32 v[108:109], v[106:107], v[106:107]
	v_cvt_pk_bf16_f32 v106, v110, v111
	v_cvt_pk_bf16_f32 v107, v112, v113
	v_pk_add_f32 v[104:105], v[104:105], 0 op_sel_hi:[1,0]
	v_max_f32_e32 v103, 0, v103
	v_max_f32_e32 v102, 0, v102
	v_max_f32_e32 v99, 0, v99
	v_max_f32_e32 v98, 0, v98
	v_max_f32_e32 v101, 0, v101
	v_max_f32_e32 v100, 0, v100
	v_cvt_pk_bf16_f32 v108, v108, v109
	v_cvt_pk_bf16_f32 v109, v116, v117
	global_store_dwordx4 v[114:115], v[106:109], off nt
	v_max_f32_e32 v105, 0, v105
	v_max_f32_e32 v104, 0, v104
	v_pk_mul_f32 v[102:103], v[102:103], v[102:103]
	v_pk_mul_f32 v[106:107], v[100:101], v[100:101]
	v_pk_mul_f32 v[100:101], v[98:99], v[98:99]
	v_cvt_pk_bf16_f32 v98, v102, v103
	v_pk_mul_f32 v[104:105], v[104:105], v[104:105]
	v_pk_add_f32 v[96:97], v[96:97], 0 op_sel_hi:[1,0]
	v_cvt_pk_bf16_f32 v99, v104, v105
	v_cvt_pk_bf16_f32 v100, v100, v101
	v_cvt_pk_bf16_f32 v101, v106, v107
	global_store_dwordx4 v[114:115], v[98:101], off offset:256 nt
	v_pk_add_f32 v[94:95], v[94:95], 0 op_sel_hi:[1,0]
	v_pk_add_f32 v[92:93], v[92:93], 0 op_sel_hi:[1,0]
	v_or_b32_e32 v98, 32, v144
	v_ashrrev_i32_e32 v99, 31, v98
	v_pk_add_f32 v[90:91], v[90:91], 0 op_sel_hi:[1,0]
	v_lshlrev_b64 v[98:99], 13, v[98:99]
	v_max_f32_e32 v95, 0, v95
	v_max_f32_e32 v94, 0, v94
	v_max_f32_e32 v97, 0, v97
	v_max_f32_e32 v96, 0, v96
	v_max_f32_e32 v91, 0, v91
	v_max_f32_e32 v90, 0, v90
	v_max_f32_e32 v93, 0, v93
	v_max_f32_e32 v92, 0, v92
	v_pk_add_f32 v[86:87], v[86:87], 0 op_sel_hi:[1,0]
	v_pk_add_f32 v[84:85], v[84:85], 0 op_sel_hi:[1,0]
	v_pk_add_f32 v[82:83], v[82:83], 0 op_sel_hi:[1,0]
	v_lshl_add_u64 v[98:99], v[142:143], 0, v[98:99]
	v_pk_mul_f32 v[96:97], v[96:97], v[96:97]
	v_pk_mul_f32 v[94:95], v[94:95], v[94:95]
	v_pk_mul_f32 v[100:101], v[92:93], v[92:93]
	v_pk_mul_f32 v[92:93], v[90:91], v[90:91]
	v_cvt_pk_bf16_f32 v90, v94, v95
	v_cvt_pk_bf16_f32 v91, v96, v97
	v_pk_add_f32 v[88:89], v[88:89], 0 op_sel_hi:[1,0]
	v_max_f32_e32 v87, 0, v87
	v_max_f32_e32 v86, 0, v86
	v_max_f32_e32 v83, 0, v83
	v_max_f32_e32 v82, 0, v82
	v_max_f32_e32 v85, 0, v85
	v_max_f32_e32 v84, 0, v84
	v_cvt_pk_bf16_f32 v92, v92, v93
	v_cvt_pk_bf16_f32 v93, v100, v101
	global_store_dwordx4 v[98:99], v[90:93], off nt
	v_max_f32_e32 v89, 0, v89
	v_max_f32_e32 v88, 0, v88
	v_pk_mul_f32 v[86:87], v[86:87], v[86:87]
	v_pk_mul_f32 v[90:91], v[84:85], v[84:85]
	v_pk_mul_f32 v[84:85], v[82:83], v[82:83]
	v_cvt_pk_bf16_f32 v82, v86, v87
	v_pk_mul_f32 v[88:89], v[88:89], v[88:89]
	v_pk_add_f32 v[80:81], v[80:81], 0 op_sel_hi:[1,0]
	v_cvt_pk_bf16_f32 v83, v88, v89
	v_cvt_pk_bf16_f32 v84, v84, v85
	v_cvt_pk_bf16_f32 v85, v90, v91
	global_store_dwordx4 v[98:99], v[82:85], off offset:256 nt
	v_pk_add_f32 v[78:79], v[78:79], 0 op_sel_hi:[1,0]
	v_pk_add_f32 v[76:77], v[76:77], 0 op_sel_hi:[1,0]
	v_or_b32_e32 v82, 48, v144
	v_ashrrev_i32_e32 v83, 31, v82
	v_pk_add_f32 v[74:75], v[74:75], 0 op_sel_hi:[1,0]
	v_lshlrev_b64 v[82:83], 13, v[82:83]
	v_max_f32_e32 v79, 0, v79
	v_max_f32_e32 v78, 0, v78
	v_max_f32_e32 v81, 0, v81
	v_max_f32_e32 v80, 0, v80
	v_max_f32_e32 v75, 0, v75
	v_max_f32_e32 v74, 0, v74
	v_max_f32_e32 v77, 0, v77
	v_max_f32_e32 v76, 0, v76
	v_pk_add_f32 v[68:69], v[68:69], 0 op_sel_hi:[1,0]
	v_pk_add_f32 v[66:67], v[66:67], 0 op_sel_hi:[1,0]
	v_lshl_add_u64 v[82:83], v[142:143], 0, v[82:83]
	v_pk_mul_f32 v[80:81], v[80:81], v[80:81]
	v_pk_mul_f32 v[78:79], v[78:79], v[78:79]
	v_pk_mul_f32 v[84:85], v[76:77], v[76:77]
	v_pk_mul_f32 v[76:77], v[74:75], v[74:75]
	v_cvt_pk_bf16_f32 v74, v78, v79
	v_cvt_pk_bf16_f32 v75, v80, v81
	v_pk_add_f32 v[72:73], v[72:73], 0 op_sel_hi:[1,0]
	v_pk_add_f32 v[70:71], v[70:71], 0 op_sel_hi:[1,0]
	v_max_f32_e32 v67, 0, v67
	v_max_f32_e32 v66, 0, v66
	v_max_f32_e32 v69, 0, v69
	v_max_f32_e32 v68, 0, v68
	v_pk_add_f32 v[62:63], v[62:63], 0 op_sel_hi:[1,0]
	v_cvt_pk_bf16_f32 v76, v76, v77
	v_cvt_pk_bf16_f32 v77, v84, v85
	global_store_dwordx4 v[82:83], v[74:77], off nt
	v_max_f32_e32 v71, 0, v71
	v_max_f32_e32 v70, 0, v70
	v_max_f32_e32 v73, 0, v73
	v_max_f32_e32 v72, 0, v72
	v_pk_mul_f32 v[74:75], v[68:69], v[68:69]
	v_pk_mul_f32 v[68:69], v[66:67], v[66:67]
	v_pk_add_f32 v[60:61], v[60:61], 0 op_sel_hi:[1,0]
	v_pk_add_f32 v[58:59], v[58:59], 0 op_sel_hi:[1,0]
	v_max_f32_e32 v63, 0, v63
	v_max_f32_e32 v62, 0, v62
	v_pk_mul_f32 v[72:73], v[72:73], v[72:73]
	v_pk_mul_f32 v[70:71], v[70:71], v[70:71]
	v_pk_add_f32 v[64:65], v[64:65], 0 op_sel_hi:[1,0]
	v_cvt_pk_bf16_f32 v66, v70, v71
	v_cvt_pk_bf16_f32 v67, v72, v73
	v_cvt_pk_bf16_f32 v68, v68, v69
	v_cvt_pk_bf16_f32 v69, v74, v75
	v_max_f32_e32 v59, 0, v59
	v_max_f32_e32 v58, 0, v58
	v_max_f32_e32 v61, 0, v61
	v_max_f32_e32 v60, 0, v60
	v_pk_mul_f32 v[62:63], v[62:63], v[62:63]
	s_mov_b32 s11, 0x100000
	global_store_dwordx4 v[82:83], v[66:69], off offset:256 nt
	v_max_f32_e32 v65, 0, v65
	v_max_f32_e32 v64, 0, v64
	v_pk_mul_f32 v[68:69], v[60:61], v[60:61]
	v_pk_mul_f32 v[60:61], v[58:59], v[58:59]
	v_cvt_pk_bf16_f32 v58, v62, v63
	v_add_co_u32_e32 v62, vcc, s11, v140
	v_pk_add_f32 v[52:53], v[52:53], 0 op_sel_hi:[1,0]
	v_pk_add_f32 v[50:51], v[50:51], 0 op_sel_hi:[1,0]
	v_pk_mul_f32 v[64:65], v[64:65], v[64:65]
	v_addc_co_u32_e32 v63, vcc, 0, v141, vcc
	v_cvt_pk_bf16_f32 v59, v64, v65
	v_pk_add_f32 v[56:57], v[56:57], 0 op_sel_hi:[1,0]
	v_pk_add_f32 v[54:55], v[54:55], 0 op_sel_hi:[1,0]
	v_max_f32_e32 v51, 0, v51
	v_max_f32_e32 v50, 0, v50
	v_max_f32_e32 v53, 0, v53
	v_max_f32_e32 v52, 0, v52
	v_pk_add_f32 v[46:47], v[46:47], 0 op_sel_hi:[1,0]
	s_mov_b64 s[20:21], 0x100000
	v_cvt_pk_bf16_f32 v60, v60, v61
	v_cvt_pk_bf16_f32 v61, v68, v69
	global_store_dwordx4 v[62:63], v[58:61], off nt
	v_max_f32_e32 v55, 0, v55
	v_max_f32_e32 v54, 0, v54
	v_max_f32_e32 v57, 0, v57
	v_max_f32_e32 v56, 0, v56
	v_pk_mul_f32 v[58:59], v[52:53], v[52:53]
	v_pk_mul_f32 v[52:53], v[50:51], v[50:51]
	v_pk_add_f32 v[44:45], v[44:45], 0 op_sel_hi:[1,0]
	v_pk_add_f32 v[42:43], v[42:43], 0 op_sel_hi:[1,0]
	v_max_f32_e32 v47, 0, v47
	v_max_f32_e32 v46, 0, v46
	v_lshl_add_u64 v[66:67], v[140:141], 0, s[20:21]
	v_pk_mul_f32 v[56:57], v[56:57], v[56:57]
	v_pk_mul_f32 v[54:55], v[54:55], v[54:55]
	v_pk_add_f32 v[48:49], v[48:49], 0 op_sel_hi:[1,0]
	v_cvt_pk_bf16_f32 v50, v54, v55
	v_cvt_pk_bf16_f32 v51, v56, v57
	v_cvt_pk_bf16_f32 v52, v52, v53
	v_cvt_pk_bf16_f32 v53, v58, v59
	v_max_f32_e32 v43, 0, v43
	v_max_f32_e32 v42, 0, v42
	v_max_f32_e32 v45, 0, v45
	v_max_f32_e32 v44, 0, v44
	v_pk_mul_f32 v[46:47], v[46:47], v[46:47]
	s_mov_b32 s11, 0x120000
	global_store_dwordx4 v[66:67], v[50:53], off offset:256 nt
	v_max_f32_e32 v49, 0, v49
	v_max_f32_e32 v48, 0, v48
	v_pk_mul_f32 v[52:53], v[44:45], v[44:45]
	v_pk_mul_f32 v[44:45], v[42:43], v[42:43]
	v_cvt_pk_bf16_f32 v42, v46, v47
	v_add_co_u32_e32 v46, vcc, s11, v140
	v_pk_add_f32 v[36:37], v[36:37], 0 op_sel_hi:[1,0]
	v_pk_add_f32 v[34:35], v[34:35], 0 op_sel_hi:[1,0]
	v_pk_mul_f32 v[48:49], v[48:49], v[48:49]
	v_addc_co_u32_e32 v47, vcc, 0, v141, vcc
	v_cvt_pk_bf16_f32 v43, v48, v49
	v_pk_add_f32 v[40:41], v[40:41], 0 op_sel_hi:[1,0]
	v_pk_add_f32 v[38:39], v[38:39], 0 op_sel_hi:[1,0]
	v_max_f32_e32 v35, 0, v35
	v_max_f32_e32 v34, 0, v34
	v_max_f32_e32 v37, 0, v37
	v_max_f32_e32 v36, 0, v36
	v_pk_add_f32 v[30:31], v[30:31], 0 op_sel_hi:[1,0]
	s_mov_b64 s[20:21], 0x120000
	v_cvt_pk_bf16_f32 v44, v44, v45
	v_cvt_pk_bf16_f32 v45, v52, v53
	global_store_dwordx4 v[46:47], v[42:45], off nt
	v_max_f32_e32 v39, 0, v39
	v_max_f32_e32 v38, 0, v38
	v_max_f32_e32 v41, 0, v41
	v_max_f32_e32 v40, 0, v40
	v_pk_mul_f32 v[42:43], v[36:37], v[36:37]
	v_pk_mul_f32 v[36:37], v[34:35], v[34:35]
	v_pk_add_f32 v[28:29], v[28:29], 0 op_sel_hi:[1,0]
	v_pk_add_f32 v[26:27], v[26:27], 0 op_sel_hi:[1,0]
	v_max_f32_e32 v31, 0, v31
	v_max_f32_e32 v30, 0, v30
	v_lshl_add_u64 v[50:51], v[140:141], 0, s[20:21]
	v_pk_mul_f32 v[40:41], v[40:41], v[40:41]
	v_pk_mul_f32 v[38:39], v[38:39], v[38:39]
	v_pk_add_f32 v[32:33], v[32:33], 0 op_sel_hi:[1,0]
	v_cvt_pk_bf16_f32 v34, v38, v39
	v_cvt_pk_bf16_f32 v35, v40, v41
	v_cvt_pk_bf16_f32 v36, v36, v37
	v_cvt_pk_bf16_f32 v37, v42, v43
	v_max_f32_e32 v27, 0, v27
	v_max_f32_e32 v26, 0, v26
	v_max_f32_e32 v29, 0, v29
	v_max_f32_e32 v28, 0, v28
	v_pk_mul_f32 v[30:31], v[30:31], v[30:31]
	s_mov_b32 s11, 0x140000
	global_store_dwordx4 v[50:51], v[34:37], off offset:256 nt
	v_max_f32_e32 v33, 0, v33
	v_max_f32_e32 v32, 0, v32
	v_pk_mul_f32 v[36:37], v[28:29], v[28:29]
	v_pk_mul_f32 v[28:29], v[26:27], v[26:27]
	v_cvt_pk_bf16_f32 v26, v30, v31
	v_add_co_u32_e32 v30, vcc, s11, v140
	v_pk_add_f32 v[20:21], v[20:21], 0 op_sel_hi:[1,0]
	v_pk_add_f32 v[18:19], v[18:19], 0 op_sel_hi:[1,0]
	v_pk_mul_f32 v[32:33], v[32:33], v[32:33]
	v_addc_co_u32_e32 v31, vcc, 0, v141, vcc
	v_cvt_pk_bf16_f32 v27, v32, v33
	v_pk_add_f32 v[24:25], v[24:25], 0 op_sel_hi:[1,0]
	v_pk_add_f32 v[22:23], v[22:23], 0 op_sel_hi:[1,0]
	v_max_f32_e32 v19, 0, v19
	v_max_f32_e32 v18, 0, v18
	v_max_f32_e32 v21, 0, v21
	v_max_f32_e32 v20, 0, v20
	v_pk_add_f32 v[14:15], v[14:15], 0 op_sel_hi:[1,0]
	s_mov_b64 s[20:21], 0x140000
	v_cvt_pk_bf16_f32 v28, v28, v29
	v_cvt_pk_bf16_f32 v29, v36, v37
	global_store_dwordx4 v[30:31], v[26:29], off nt
	v_max_f32_e32 v23, 0, v23
	v_max_f32_e32 v22, 0, v22
	v_max_f32_e32 v25, 0, v25
	v_max_f32_e32 v24, 0, v24
	v_pk_mul_f32 v[26:27], v[20:21], v[20:21]
	v_pk_mul_f32 v[20:21], v[18:19], v[18:19]
	v_pk_add_f32 v[12:13], v[12:13], 0 op_sel_hi:[1,0]
	v_pk_add_f32 v[10:11], v[10:11], 0 op_sel_hi:[1,0]
	v_max_f32_e32 v15, 0, v15
	v_max_f32_e32 v14, 0, v14
	v_lshl_add_u64 v[34:35], v[140:141], 0, s[20:21]
	v_pk_mul_f32 v[24:25], v[24:25], v[24:25]
	v_pk_mul_f32 v[22:23], v[22:23], v[22:23]
	v_pk_add_f32 v[16:17], v[16:17], 0 op_sel_hi:[1,0]
	v_cvt_pk_bf16_f32 v18, v22, v23
	v_cvt_pk_bf16_f32 v19, v24, v25
	v_cvt_pk_bf16_f32 v20, v20, v21
	v_cvt_pk_bf16_f32 v21, v26, v27
	v_max_f32_e32 v11, 0, v11
	v_max_f32_e32 v10, 0, v10
	v_max_f32_e32 v13, 0, v13
	v_max_f32_e32 v12, 0, v12
	v_pk_mul_f32 v[14:15], v[14:15], v[14:15]
	s_mov_b32 s11, 0x160000
	global_store_dwordx4 v[34:35], v[18:21], off offset:256 nt
	v_max_f32_e32 v17, 0, v17
	v_max_f32_e32 v16, 0, v16
	v_pk_mul_f32 v[20:21], v[12:13], v[12:13]
	v_pk_mul_f32 v[12:13], v[10:11], v[10:11]
	v_cvt_pk_bf16_f32 v10, v14, v15
	v_add_co_u32_e32 v14, vcc, s11, v140
	v_pk_add_f32 v[4:5], v[4:5], 0 op_sel_hi:[1,0]
	v_pk_add_f32 v[2:3], v[2:3], 0 op_sel_hi:[1,0]
	s_mov_b64 s[20:21], 0x160000
	v_pk_mul_f32 v[16:17], v[16:17], v[16:17]
	v_addc_co_u32_e32 v15, vcc, 0, v141, vcc
	v_cvt_pk_bf16_f32 v11, v16, v17
	v_pk_add_f32 v[8:9], v[8:9], 0 op_sel_hi:[1,0]
	v_pk_add_f32 v[6:7], v[6:7], 0 op_sel_hi:[1,0]
	v_max_f32_e32 v3, 0, v3
	v_max_f32_e32 v2, 0, v2
	v_max_f32_e32 v5, 0, v5
	v_max_f32_e32 v4, 0, v4
	v_lshl_add_u64 v[18:19], v[140:141], 0, s[20:21]
	v_cvt_pk_bf16_f32 v12, v12, v13
	v_cvt_pk_bf16_f32 v13, v20, v21
	global_store_dwordx4 v[14:15], v[10:13], off nt
	v_max_f32_e32 v7, 0, v7
	v_max_f32_e32 v6, 0, v6
	v_max_f32_e32 v9, 0, v9
	v_max_f32_e32 v8, 0, v8
	v_pk_mul_f32 v[10:11], v[4:5], v[4:5]
	v_pk_mul_f32 v[4:5], v[2:3], v[2:3]
	s_andn2_b64 vcc, exec, s[0:1]
	s_mov_b64 s[0:1], -1
	s_movk_i32 s55, 0xf000
	v_pk_mul_f32 v[8:9], v[8:9], v[8:9]
	v_pk_mul_f32 v[6:7], v[6:7], v[6:7]
	s_nop 0
	v_cvt_pk_bf16_f32 v2, v6, v7
	v_cvt_pk_bf16_f32 v3, v8, v9
	v_cvt_pk_bf16_f32 v4, v4, v5
	v_cvt_pk_bf16_f32 v5, v10, v11
	global_store_dwordx4 v[18:19], v[2:5], off offset:256 nt
	s_mov_b32 s98, 1
	s_cbranch_vccnz .LBB0_35
	s_andn2_b64 vcc, exec, s[4:5]
	s_cbranch_vccnz .LBB0_34
	s_barrier
	s_branch .LBB0_34
.Lrelax_ff1_w1:
	s_waitcnt vmcnt(24)
	s_branch .Lback_ff1_w1
.Lrelax_ff1_w2:
	s_waitcnt vmcnt(24)
	s_branch .Lback_ff1_w2

.LBB0_79:
	s_add_u32 s22, s20, 0xfffc0080
	s_addc_u32 s23, s21, -1
	s_add_i32 s55, 0, 0x10000
	s_cmp_eq_u32 s49, 12
	s_cselect_b32 s25, s13, s23
	s_cselect_b32 s24, s45, s22
	s_cselect_b32 s23, s11, s48
	s_cselect_b32 s22, s46, s47
	s_add_i32 s58, 0, 0x14000
	v_add_u32_e32 v134, s55, v176
	v_add_u32_e32 v179, s58, v176
	ds_read_b128 v[122:125], v134
	ds_read_b128 v[126:129], v134 offset:1024
	ds_read_b128 v[130:133], v134 offset:2048
	ds_read_b128 v[134:137], v134 offset:3072
	ds_read_b128 v[146:149], v179
	ds_read_b128 v[154:157], v179 offset:1024
	ds_read_b128 v[172:175], v179 offset:2048
	ds_read_b128 v[180:183], v179 offset:3072
	v_lshl_add_u64 v[212:213], s[20:21], 0, v[170:171]
	s_add_i32 m0, s19, 0xc000
	ds_read_b128 v[184:187], v178
	ds_read_b128 v[188:191], v178 offset:1024
	ds_read_b128 v[192:195], v178 offset:2048
	ds_read_b128 v[196:199], v178 offset:3072
	ds_read_b128 v[200:203], v178 offset:4096
	ds_read_b128 v[204:207], v178 offset:5120
	ds_read_b128 v[208:211], v178 offset:6144
	ds_read_b128 v[222:225], v178 offset:7168
	s_cmp_lg_u32 s98, 0
	s_cbranch_scc1 .Lgc_skip_g2
	global_load_lds_dwordx4 v[212:213], off
	v_lshl_add_u64 v[212:213], s[20:21], 0, v[168:169]
	s_add_i32 m0, s19, 0xe000
	s_nop 0
	global_load_lds_dwordx4 v[212:213], off

.Lback_g2_w2:
	s_waitcnt lgkmcnt(0)
	s_barrier
	s_setprio 1
	s_waitcnt lgkmcnt(0)
	v_mfma_f32_16x16x32_bf16 v[62:65], v[122:125], v[184:187], v[62:65]
	v_mfma_f32_16x16x32_bf16 v[58:61], v[130:133], v[184:187], v[58:61]
	v_mfma_f32_16x16x32_bf16 v[54:57], v[122:125], v[192:195], v[54:57]
	v_mfma_f32_16x16x32_bf16 v[42:45], v[130:133], v[192:195], v[42:45]
	v_mfma_f32_16x16x32_bf16 v[34:37], v[122:125], v[200:203], v[34:37]
	v_mfma_f32_16x16x32_bf16 v[26:29], v[130:133], v[200:203], v[26:29]
	v_mfma_f32_16x16x32_bf16 v[22:25], v[122:125], v[208:211], v[22:25]
	v_mfma_f32_16x16x32_bf16 v[10:13], v[130:133], v[208:211], v[10:13]
	v_mfma_f32_16x16x32_bf16 v[62:65], v[126:129], v[188:191], v[62:65]
	v_mfma_f32_16x16x32_bf16 v[58:61], v[134:137], v[188:191], v[58:61]
	v_mfma_f32_16x16x32_bf16 v[54:57], v[126:129], v[196:199], v[54:57]
	v_mfma_f32_16x16x32_bf16 v[42:45], v[134:137], v[196:199], v[42:45]
	v_mfma_f32_16x16x32_bf16 v[34:37], v[126:129], v[204:207], v[34:37]
	v_mfma_f32_16x16x32_bf16 v[26:29], v[134:137], v[204:207], v[26:29]
	v_mfma_f32_16x16x32_bf16 v[22:25], v[126:129], v[222:225], v[22:25]
	v_mfma_f32_16x16x32_bf16 v[10:13], v[134:137], v[222:225], v[10:13]
	s_setprio 0
	s_setprio 1
	v_mfma_f32_16x16x32_bf16 v[50:53], v[146:149], v[184:187], v[50:53]
	v_mfma_f32_16x16x32_bf16 v[46:49], v[172:175], v[184:187], v[46:49]
	v_mfma_f32_16x16x32_bf16 v[38:41], v[146:149], v[192:195], v[38:41]
	v_mfma_f32_16x16x32_bf16 v[30:33], v[172:175], v[192:195], v[30:33]
	v_mfma_f32_16x16x32_bf16 v[18:21], v[146:149], v[200:203], v[18:21]
	v_mfma_f32_16x16x32_bf16 v[14:17], v[172:175], v[200:203], v[14:17]
	v_mfma_f32_16x16x32_bf16 v[6:9], v[146:149], v[208:211], v[6:9]
	v_mfma_f32_16x16x32_bf16 v[2:5], v[172:175], v[208:211], v[2:5]
	v_mfma_f32_16x16x32_bf16 v[50:53], v[154:157], v[188:191], v[50:53]
	v_mfma_f32_16x16x32_bf16 v[46:49], v[180:183], v[188:191], v[46:49]
	v_mfma_f32_16x16x32_bf16 v[38:41], v[154:157], v[196:199], v[38:41]
	v_mfma_f32_16x16x32_bf16 v[30:33], v[180:183], v[196:199], v[30:33]
	v_mfma_f32_16x16x32_bf16 v[18:21], v[154:157], v[204:207], v[18:21]
	v_mfma_f32_16x16x32_bf16 v[14:17], v[180:183], v[204:207], v[14:17]
	v_mfma_f32_16x16x32_bf16 v[6:9], v[154:157], v[222:225], v[6:9]
	v_mfma_f32_16x16x32_bf16 v[2:5], v[180:183], v[222:225], v[2:5]
	s_setprio 0
	s_barrier
	s_add_i32 s55, 0, 0x18000
	s_add_i32 s56, 0, 0x1c000
	v_add_u32_e32 v134, s55, v176
	v_add_u32_e32 v179, s56, v176
	ds_read_b128 v[122:125], v134
	ds_read_b128 v[126:129], v134 offset:1024
	ds_read_b128 v[130:133], v134 offset:2048
	ds_read_b128 v[134:137], v134 offset:3072
	ds_read_b128 v[146:149], v179
	ds_read_b128 v[154:157], v179 offset:1024
	ds_read_b128 v[172:175], v179 offset:2048
	ds_read_b128 v[180:183], v179 offset:3072
	s_add_u32 s24, s24, 0x40000
	s_addc_u32 s25, s25, 0
	s_mov_b32 m0, s31
	v_lshl_add_u64 v[232:233], s[24:25], 0, v[162:163]
	ds_read_b128 v[184:187], v178 offset:32768
	ds_read_b128 v[188:191], v178 offset:33792
	ds_read_b128 v[192:195], v178 offset:34816
	ds_read_b128 v[196:199], v178 offset:35840
	ds_read_b128 v[200:203], v178 offset:36864
	ds_read_b128 v[204:207], v178 offset:37888
	ds_read_b128 v[208:211], v178 offset:38912
	ds_read_b128 v[222:225], v178 offset:39936
	global_load_lds_dwordx4 v[232:233], off
	v_lshl_add_u64 v[232:233], s[24:25], 0, v[164:165]
	s_mov_b32 m0, s37
	s_nop 0
	global_load_lds_dwordx4 v[232:233], off
	s_cmp_lg_u32 s98, 0
	s_cbranch_scc1 .Lrelax_g2_w3
	s_waitcnt vmcnt(8)
.Lback_g2_w3:
	s_waitcnt lgkmcnt(0)
	s_barrier
	s_setprio 1
	s_waitcnt lgkmcnt(0)
	v_mfma_f32_16x16x32_bf16 v[142:145], v[122:125], v[184:187], v[142:145]
	v_mfma_f32_16x16x32_bf16 v[138:141], v[130:133], v[184:187], v[138:141]
	v_mfma_f32_16x16x32_bf16 v[118:121], v[122:125], v[192:195], v[118:121]
	v_mfma_f32_16x16x32_bf16 v[106:109], v[130:133], v[192:195], v[106:109]
	v_mfma_f32_16x16x32_bf16 v[98:101], v[122:125], v[200:203], v[98:101]
	v_mfma_f32_16x16x32_bf16 v[90:93], v[130:133], v[200:203], v[90:93]
	v_mfma_f32_16x16x32_bf16 v[86:89], v[122:125], v[208:211], v[86:89]
	v_mfma_f32_16x16x32_bf16 v[74:77], v[130:133], v[208:211], v[74:77]
	v_mfma_f32_16x16x32_bf16 v[142:145], v[126:129], v[188:191], v[142:145]
	v_mfma_f32_16x16x32_bf16 v[138:141], v[134:137], v[188:191], v[138:141]
	v_mfma_f32_16x16x32_bf16 v[118:121], v[126:129], v[196:199], v[118:121]
	v_mfma_f32_16x16x32_bf16 v[106:109], v[134:137], v[196:199], v[106:109]
	v_mfma_f32_16x16x32_bf16 v[98:101], v[126:129], v[204:207], v[98:101]
	v_mfma_f32_16x16x32_bf16 v[90:93], v[134:137], v[204:207], v[90:93]
	v_mfma_f32_16x16x32_bf16 v[86:89], v[126:129], v[222:225], v[86:89]
	v_mfma_f32_16x16x32_bf16 v[74:77], v[134:137], v[222:225], v[74:77]
	s_setprio 0
	s_setprio 1
	v_mfma_f32_16x16x32_bf16 v[114:117], v[146:149], v[184:187], v[114:117]
	v_mfma_f32_16x16x32_bf16 v[110:113], v[172:175], v[184:187], v[110:113]
	v_mfma_f32_16x16x32_bf16 v[102:105], v[146:149], v[192:195], v[102:105]
	v_mfma_f32_16x16x32_bf16 v[94:97], v[172:175], v[192:195], v[94:97]
	v_mfma_f32_16x16x32_bf16 v[82:85], v[146:149], v[200:203], v[82:85]
	v_mfma_f32_16x16x32_bf16 v[78:81], v[172:175], v[200:203], v[78:81]
	v_mfma_f32_16x16x32_bf16 v[70:73], v[146:149], v[208:211], v[70:73]
	v_mfma_f32_16x16x32_bf16 v[66:69], v[172:175], v[208:211], v[66:69]
	v_mfma_f32_16x16x32_bf16 v[114:117], v[154:157], v[188:191], v[114:117]
	v_mfma_f32_16x16x32_bf16 v[110:113], v[180:183], v[188:191], v[110:113]
	v_mfma_f32_16x16x32_bf16 v[102:105], v[154:157], v[196:199], v[102:105]
	v_mfma_f32_16x16x32_bf16 v[94:97], v[180:183], v[196:199], v[94:97]
	v_mfma_f32_16x16x32_bf16 v[82:85], v[154:157], v[204:207], v[82:85]
	v_mfma_f32_16x16x32_bf16 v[78:81], v[180:183], v[204:207], v[78:81]
	v_mfma_f32_16x16x32_bf16 v[70:73], v[154:157], v[222:225], v[70:73]
	v_mfma_f32_16x16x32_bf16 v[66:69], v[180:183], v[222:225], v[66:69]
	s_setprio 0
	s_barrier
	s_add_i32 s24, s55, s29
	v_lshl_add_u64 v[212:213], v[212:213], 0, s[96:97]
	s_mov_b32 m0, s24
	ds_read_b128 v[184:187], v178 offset:49152
	ds_read_b128 v[188:191], v178 offset:50176
	ds_read_b128 v[192:195], v178 offset:51200
	ds_read_b128 v[196:199], v178 offset:52224
	ds_read_b128 v[200:203], v178 offset:53248
	ds_read_b128 v[204:207], v178 offset:54272
	ds_read_b128 v[208:211], v178 offset:55296
	ds_read_b128 v[222:225], v178 offset:56320
	global_load_lds_dwordx4 v[212:213], off
	s_add_i32 m0, s24, 0x2000
	s_add_u32 s22, s22, 0x40080
	v_lshl_add_u64 v[212:213], v[226:227], 0, s[96:97]
	s_addc_u32 s23, s23, 0
	s_add_i32 s24, s56, s29
	global_load_lds_dwordx4 v[212:213], off
	v_lshl_add_u64 v[212:213], s[22:23], 0, v[0:1]
	s_mov_b32 m0, s24
	s_nop 0
	global_load_lds_dwordx4 v[212:213], off
	v_lshl_add_u64 v[212:213], s[22:23], 0, v[166:167]
	s_add_i32 m0, s24, 0x2000
	s_nop 0
	global_load_lds_dwordx4 v[212:213], off
	v_lshl_add_u64 v[212:213], v[228:229], 0, s[96:97]
	s_mov_b32 m0, s40
	s_nop 0
	global_load_lds_dwordx4 v[212:213], off
	v_lshl_add_u64 v[212:213], v[230:231], 0, s[96:97]
	s_mov_b32 m0, s41
	s_nop 0
	global_load_lds_dwordx4 v[212:213], off
	s_waitcnt vmcnt(8)
	s_waitcnt lgkmcnt(0)
	s_barrier
	s_setprio 1
	s_waitcnt lgkmcnt(0)
	v_mfma_f32_16x16x32_bf16 v[62:65], v[122:125], v[184:187], v[62:65]
	v_mfma_f32_16x16x32_bf16 v[58:61], v[130:133], v[184:187], v[58:61]
	v_mfma_f32_16x16x32_bf16 v[54:57], v[122:125], v[192:195], v[54:57]
	v_mfma_f32_16x16x32_bf16 v[42:45], v[130:133], v[192:195], v[42:45]
	v_mfma_f32_16x16x32_bf16 v[34:37], v[122:125], v[200:203], v[34:37]
	v_mfma_f32_16x16x32_bf16 v[26:29], v[130:133], v[200:203], v[26:29]
	v_mfma_f32_16x16x32_bf16 v[22:25], v[122:125], v[208:211], v[22:25]
	v_mfma_f32_16x16x32_bf16 v[10:13], v[130:133], v[208:211], v[10:13]
	v_mfma_f32_16x16x32_bf16 v[62:65], v[126:129], v[188:191], v[62:65]
	v_mfma_f32_16x16x32_bf16 v[58:61], v[134:137], v[188:191], v[58:61]
	v_mfma_f32_16x16x32_bf16 v[54:57], v[126:129], v[196:199], v[54:57]
	v_mfma_f32_16x16x32_bf16 v[42:45], v[134:137], v[196:199], v[42:45]
	v_mfma_f32_16x16x32_bf16 v[34:37], v[126:129], v[204:207], v[34:37]
	v_mfma_f32_16x16x32_bf16 v[26:29], v[134:137], v[204:207], v[26:29]
	v_mfma_f32_16x16x32_bf16 v[22:25], v[126:129], v[222:225], v[22:25]
	v_mfma_f32_16x16x32_bf16 v[10:13], v[134:137], v[222:225], v[10:13]
	s_setprio 0
	s_setprio 1
	v_mfma_f32_16x16x32_bf16 v[50:53], v[146:149], v[184:187], v[50:53]
	v_mfma_f32_16x16x32_bf16 v[46:49], v[172:175], v[184:187], v[46:49]
	v_mfma_f32_16x16x32_bf16 v[38:41], v[146:149], v[192:195], v[38:41]
	v_mfma_f32_16x16x32_bf16 v[30:33], v[172:175], v[192:195], v[30:33]
	v_mfma_f32_16x16x32_bf16 v[18:21], v[146:149], v[200:203], v[18:21]
	v_mfma_f32_16x16x32_bf16 v[14:17], v[172:175], v[200:203], v[14:17]
	v_mfma_f32_16x16x32_bf16 v[6:9], v[146:149], v[208:211], v[6:9]
	v_mfma_f32_16x16x32_bf16 v[2:5], v[172:175], v[208:211], v[2:5]
	v_mfma_f32_16x16x32_bf16 v[50:53], v[154:157], v[188:191], v[50:53]
	v_mfma_f32_16x16x32_bf16 v[46:49], v[180:183], v[188:191], v[46:49]
	v_mfma_f32_16x16x32_bf16 v[38:41], v[154:157], v[196:199], v[38:41]
	v_mfma_f32_16x16x32_bf16 v[30:33], v[180:183], v[196:199], v[30:33]
	v_mfma_f32_16x16x32_bf16 v[18:21], v[154:157], v[204:207], v[18:21]
	v_mfma_f32_16x16x32_bf16 v[14:17], v[180:183], v[204:207], v[14:17]
	v_mfma_f32_16x16x32_bf16 v[6:9], v[154:157], v[222:225], v[6:9]
	v_mfma_f32_16x16x32_bf16 v[2:5], v[180:183], v[222:225], v[2:5]
	s_setprio 0
	s_barrier
	s_add_i32 s49, s49, 2
	s_add_u32 s47, s47, 0x100
	s_addc_u32 s48, s48, 0
	s_add_u32 s20, s20, 0x100
	s_addc_u32 s21, s21, 0
	s_cmp_gt_u32 s49, 13
	s_cbranch_scc0 .LBB0_79
	s_add_u32 s20, s45, 0x40080
	s_addc_u32 s21, s13, 0
	s_and_b64 vcc, exec, s[8:9]
	s_movk_i32 s46, 0xd000
	s_movk_i32 s47, 0xec00
	s_cbranch_vccz .LBB0_82
	s_barrier
.LBB0_82:
	v_lshl_add_u64 v[212:213], s[20:21], 0, v[170:171]
	s_add_i32 m0, s19, 0xc000
	s_nop 0
	global_load_lds_dwordx4 v[212:213], off
	v_lshl_add_u64 v[212:213], s[20:21], 0, v[168:169]
	s_add_i32 m0, s19, 0xe000
	s_nop 0
	global_load_lds_dwordx4 v[212:213], off
	v_lshl_add_u32 v172, s18, 8, v159
	v_lshl_or_b32 v122, s44, 8, v177
	v_ashrrev_i32_e32 v173, 31, v172
	v_ashrrev_i32_e32 v123, 31, v122
	v_lshlrev_b64 v[124:125], 11, v[172:173]
	v_lshl_add_u64 v[124:125], s[4:5], 0, v[124:125]
	v_lshlrev_b64 v[174:175], 1, v[122:123]
	s_ashr_i32 s11, s18, 4
	v_lshl_add_u64 v[154:155], v[124:125], 0, v[174:175]
	s_mul_hi_i32 s13, s11, 0x6000
	s_mulk_i32 s11, 0x6000
	s_add_u32 s20, s38, s11
	s_addc_u32 s21, s39, s13
	v_lshl_add_u64 v[122:123], v[122:123], 2, s[20:21]
	global_load_dwordx4 v[134:137], v[122:123], off
	global_load_dwordx4 v[130:133], v[122:123], off offset:16
	global_load_dwordx4 v[126:129], v[122:123], off offset:512
	s_nop 0
	global_load_dwordx4 v[122:125], v[122:123], off offset:528
	v_mov_b64_e32 v[172:173], v[154:155]
	v_mov_b64_e32 v[174:175], v[172:173]
	global_load_dwordx4 v[146:149], v[174:175], off
	global_load_dwordx4 v[154:157], v[174:175], off offset:256
	s_mov_b32 s20, 0x8000
	s_mov_b32 s21, 0
	v_lshl_add_u64 v[174:175], v[172:173], 0, s[20:21]
	global_load_dwordx4 v[180:183], v[174:175], off
	global_load_dwordx4 v[184:187], v[174:175], off offset:256
	s_mov_b32 s20, 0x10000
	s_mov_b32 s21, 0
	v_lshl_add_u64 v[174:175], v[172:173], 0, s[20:21]
	global_load_dwordx4 v[188:191], v[174:175], off
	global_load_dwordx4 v[192:195], v[174:175], off offset:256
	s_mov_b32 s20, 0x18000
	s_mov_b32 s21, 0
	v_lshl_add_u64 v[174:175], v[172:173], 0, s[20:21]
	global_load_dwordx4 v[196:199], v[174:175], off
	global_load_dwordx4 v[200:203], v[174:175], off offset:256
	s_mov_b32 s20, 0x40000
	s_mov_b32 s21, 0
	v_lshl_add_u64 v[174:175], v[172:173], 0, s[20:21]
	global_load_dwordx4 v[204:207], v[174:175], off
	global_load_dwordx4 v[208:211], v[174:175], off offset:256
	s_mov_b32 s20, 0x48000
	s_mov_b32 s21, 0
	v_lshl_add_u64 v[174:175], v[172:173], 0, s[20:21]
	global_load_dwordx4 v[222:225], v[174:175], off
	global_load_dwordx4 v[226:229], v[174:175], off offset:256
	s_mov_b32 s20, 0x50000
	s_mov_b32 s21, 0
	v_lshl_add_u64 v[174:175], v[172:173], 0, s[20:21]
	global_load_dwordx4 v[230:233], v[174:175], off
	global_load_dwordx4 v[234:237], v[174:175], off offset:256
	s_mov_b32 s20, 0x58000
	s_mov_b32 s21, 0
	v_lshl_add_u64 v[174:175], v[172:173], 0, s[20:21]
	global_load_dwordx4 v[240:243], v[174:175], off
	global_load_dwordx4 v[244:247], v[174:175], off offset:256
	v_mov_b64_e32 v[174:175], v[172:173]
	s_waitcnt vmcnt(14)
	v_lshlrev_b32_e32 v212, 16, v146
	v_and_b32_e32 v213, 0xffff0000, v146
	v_lshlrev_b32_e32 v248, 16, v148
	v_and_b32_e32 v249, 0xffff0000, v148
	v_lshlrev_b32_e32 v146, 16, v147
	v_and_b32_e32 v147, 0xffff0000, v147
	v_lshlrev_b32_e32 v148, 16, v149
	v_and_b32_e32 v149, 0xffff0000, v149
	v_pk_fma_f32 v[142:143], v[142:143], v[134:135], v[212:213]
	v_pk_fma_f32 v[138:139], v[138:139], v[130:131], v[248:249]
	v_pk_fma_f32 v[144:145], v[144:145], v[136:137], v[146:147]
	v_pk_fma_f32 v[140:141], v[140:141], v[132:133], v[148:149]
	v_cvt_pk_bf16_f32 v146, v142, v143
	v_cvt_pk_bf16_f32 v147, v144, v145
	v_cvt_pk_bf16_f32 v148, v138, v139
	v_cvt_pk_bf16_f32 v149, v140, v141
	global_store_dwordx4 v[174:175], v[146:149], off
	v_lshlrev_b32_e32 v212, 16, v154
	v_and_b32_e32 v213, 0xffff0000, v154
	v_lshlrev_b32_e32 v248, 16, v156
	v_and_b32_e32 v249, 0xffff0000, v156
	v_lshlrev_b32_e32 v154, 16, v155
	v_and_b32_e32 v155, 0xffff0000, v155
	v_lshlrev_b32_e32 v156, 16, v157
	v_and_b32_e32 v157, 0xffff0000, v157
	v_pk_fma_f32 v[114:115], v[114:115], v[126:127], v[212:213]
	v_pk_fma_f32 v[110:111], v[110:111], v[122:123], v[248:249]
	v_pk_fma_f32 v[116:117], v[116:117], v[128:129], v[154:155]
	v_pk_fma_f32 v[112:113], v[112:113], v[124:125], v[156:157]
	v_cvt_pk_bf16_f32 v154, v114, v115
	v_cvt_pk_bf16_f32 v155, v116, v117
	v_cvt_pk_bf16_f32 v156, v110, v111
	v_cvt_pk_bf16_f32 v157, v112, v113
	global_store_dwordx4 v[174:175], v[154:157], off offset:256
	s_mov_b32 s20, 0x8000
	s_mov_b32 s21, 0
	v_lshl_add_u64 v[174:175], v[172:173], 0, s[20:21]
	s_waitcnt vmcnt(14)
	v_lshlrev_b32_e32 v212, 16, v180
	v_and_b32_e32 v213, 0xffff0000, v180
	v_lshlrev_b32_e32 v248, 16, v182
	v_and_b32_e32 v249, 0xffff0000, v182
	v_lshlrev_b32_e32 v180, 16, v181
	v_and_b32_e32 v181, 0xffff0000, v181
	v_lshlrev_b32_e32 v182, 16, v183
	v_and_b32_e32 v183, 0xffff0000, v183
	v_pk_fma_f32 v[118:119], v[118:119], v[134:135], v[212:213]
	v_pk_fma_f32 v[106:107], v[106:107], v[130:131], v[248:249]
	v_pk_fma_f32 v[120:121], v[120:121], v[136:137], v[180:181]
	v_pk_fma_f32 v[108:109], v[108:109], v[132:133], v[182:183]
	v_cvt_pk_bf16_f32 v180, v118, v119
	v_cvt_pk_bf16_f32 v181, v120, v121
	v_cvt_pk_bf16_f32 v182, v106, v107
	v_cvt_pk_bf16_f32 v183, v108, v109
	global_store_dwordx4 v[174:175], v[180:183], off
	v_lshlrev_b32_e32 v212, 16, v184
	v_and_b32_e32 v213, 0xffff0000, v184
	v_lshlrev_b32_e32 v248, 16, v186
	v_and_b32_e32 v249, 0xffff0000, v186
	v_lshlrev_b32_e32 v184, 16, v185
	v_and_b32_e32 v185, 0xffff0000, v185
	v_lshlrev_b32_e32 v186, 16, v187
	v_and_b32_e32 v187, 0xffff0000, v187
	v_pk_fma_f32 v[102:103], v[102:103], v[126:127], v[212:213]
	v_pk_fma_f32 v[94:95], v[94:95], v[122:123], v[248:249]
	v_pk_fma_f32 v[104:105], v[104:105], v[128:129], v[184:185]
	v_pk_fma_f32 v[96:97], v[96:97], v[124:125], v[186:187]
	v_cvt_pk_bf16_f32 v184, v102, v103
	v_cvt_pk_bf16_f32 v185, v104, v105
	v_cvt_pk_bf16_f32 v186, v94, v95
	v_cvt_pk_bf16_f32 v187, v96, v97
	global_store_dwordx4 v[174:175], v[184:187], off offset:256
	s_mov_b32 s20, 0x10000
	s_mov_b32 s21, 0
	v_lshl_add_u64 v[174:175], v[172:173], 0, s[20:21]
	s_waitcnt vmcnt(14)
	v_lshlrev_b32_e32 v212, 16, v188
	v_and_b32_e32 v213, 0xffff0000, v188
	v_lshlrev_b32_e32 v248, 16, v190
	v_and_b32_e32 v249, 0xffff0000, v190
	v_lshlrev_b32_e32 v188, 16, v189
	v_and_b32_e32 v189, 0xffff0000, v189
	v_lshlrev_b32_e32 v190, 16, v191
	v_and_b32_e32 v191, 0xffff0000, v191
	v_pk_fma_f32 v[98:99], v[98:99], v[134:135], v[212:213]
	v_pk_fma_f32 v[90:91], v[90:91], v[130:131], v[248:249]
	v_pk_fma_f32 v[100:101], v[100:101], v[136:137], v[188:189]
	v_pk_fma_f32 v[92:93], v[92:93], v[132:133], v[190:191]
	v_cvt_pk_bf16_f32 v188, v98, v99
	v_cvt_pk_bf16_f32 v189, v100, v101
	v_cvt_pk_bf16_f32 v190, v90, v91
	v_cvt_pk_bf16_f32 v191, v92, v93
	global_store_dwordx4 v[174:175], v[188:191], off
	v_lshlrev_b32_e32 v212, 16, v192
	v_and_b32_e32 v213, 0xffff0000, v192
	v_lshlrev_b32_e32 v248, 16, v194
	v_and_b32_e32 v249, 0xffff0000, v194
	v_lshlrev_b32_e32 v192, 16, v193
	v_and_b32_e32 v193, 0xffff0000, v193
	v_lshlrev_b32_e32 v194, 16, v195
	v_and_b32_e32 v195, 0xffff0000, v195
	v_pk_fma_f32 v[82:83], v[82:83], v[126:127], v[212:213]
	v_pk_fma_f32 v[78:79], v[78:79], v[122:123], v[248:249]
	v_pk_fma_f32 v[84:85], v[84:85], v[128:129], v[192:193]
	v_pk_fma_f32 v[80:81], v[80:81], v[124:125], v[194:195]
	v_cvt_pk_bf16_f32 v192, v82, v83
	v_cvt_pk_bf16_f32 v193, v84, v85
	v_cvt_pk_bf16_f32 v194, v78, v79
	v_cvt_pk_bf16_f32 v195, v80, v81
	global_store_dwordx4 v[174:175], v[192:195], off offset:256
	s_mov_b32 s20, 0x18000
	s_mov_b32 s21, 0
	v_lshl_add_u64 v[174:175], v[172:173], 0, s[20:21]
	s_waitcnt vmcnt(14)
	v_lshlrev_b32_e32 v212, 16, v196
	v_and_b32_e32 v213, 0xffff0000, v196
	v_lshlrev_b32_e32 v248, 16, v198
	v_and_b32_e32 v249, 0xffff0000, v198
	v_lshlrev_b32_e32 v196, 16, v197
	v_and_b32_e32 v197, 0xffff0000, v197
	v_lshlrev_b32_e32 v198, 16, v199
	v_and_b32_e32 v199, 0xffff0000, v199
	v_pk_fma_f32 v[86:87], v[86:87], v[134:135], v[212:213]
	v_pk_fma_f32 v[74:75], v[74:75], v[130:131], v[248:249]
	v_pk_fma_f32 v[88:89], v[88:89], v[136:137], v[196:197]
	v_pk_fma_f32 v[76:77], v[76:77], v[132:133], v[198:199]
	v_cvt_pk_bf16_f32 v196, v86, v87
	v_cvt_pk_bf16_f32 v197, v88, v89
	v_cvt_pk_bf16_f32 v198, v74, v75
	v_cvt_pk_bf16_f32 v199, v76, v77
	global_store_dwordx4 v[174:175], v[196:199], off
	v_lshlrev_b32_e32 v212, 16, v200
	v_and_b32_e32 v213, 0xffff0000, v200
	v_lshlrev_b32_e32 v248, 16, v202
	v_and_b32_e32 v249, 0xffff0000, v202
	v_lshlrev_b32_e32 v200, 16, v201
	v_and_b32_e32 v201, 0xffff0000, v201
	v_lshlrev_b32_e32 v202, 16, v203
	v_and_b32_e32 v203, 0xffff0000, v203
	v_pk_fma_f32 v[70:71], v[70:71], v[126:127], v[212:213]
	v_pk_fma_f32 v[66:67], v[66:67], v[122:123], v[248:249]
	v_pk_fma_f32 v[72:73], v[72:73], v[128:129], v[200:201]
	v_pk_fma_f32 v[68:69], v[68:69], v[124:125], v[202:203]
	v_cvt_pk_bf16_f32 v200, v70, v71
	v_cvt_pk_bf16_f32 v201, v72, v73
	v_cvt_pk_bf16_f32 v202, v66, v67
	v_cvt_pk_bf16_f32 v203, v68, v69
	global_store_dwordx4 v[174:175], v[200:203], off offset:256
	s_mov_b32 s20, 0x40000
	s_mov_b32 s21, 0
	v_lshl_add_u64 v[174:175], v[172:173], 0, s[20:21]
	s_waitcnt vmcnt(14)
	v_lshlrev_b32_e32 v212, 16, v204
	v_and_b32_e32 v213, 0xffff0000, v204
	v_lshlrev_b32_e32 v248, 16, v206
	v_and_b32_e32 v249, 0xffff0000, v206
	v_lshlrev_b32_e32 v204, 16, v205
	v_and_b32_e32 v205, 0xffff0000, v205
	v_lshlrev_b32_e32 v206, 16, v207
	v_and_b32_e32 v207, 0xffff0000, v207
	v_pk_fma_f32 v[62:63], v[62:63], v[134:135], v[212:213]
	v_pk_fma_f32 v[58:59], v[58:59], v[130:131], v[248:249]
	v_pk_fma_f32 v[64:65], v[64:65], v[136:137], v[204:205]
	v_pk_fma_f32 v[60:61], v[60:61], v[132:133], v[206:207]
	v_cvt_pk_bf16_f32 v204, v62, v63
	v_cvt_pk_bf16_f32 v205, v64, v65
	v_cvt_pk_bf16_f32 v206, v58, v59
	v_cvt_pk_bf16_f32 v207, v60, v61
	global_store_dwordx4 v[174:175], v[204:207], off
	v_lshlrev_b32_e32 v212, 16, v208
	v_and_b32_e32 v213, 0xffff0000, v208
	v_lshlrev_b32_e32 v248, 16, v210
	v_and_b32_e32 v249, 0xffff0000, v210
	v_lshlrev_b32_e32 v208, 16, v209
	v_and_b32_e32 v209, 0xffff0000, v209
	v_lshlrev_b32_e32 v210, 16, v211
	v_and_b32_e32 v211, 0xffff0000, v211
	v_pk_fma_f32 v[50:51], v[50:51], v[126:127], v[212:213]
	v_pk_fma_f32 v[46:47], v[46:47], v[122:123], v[248:249]
	v_pk_fma_f32 v[52:53], v[52:53], v[128:129], v[208:209]
	v_pk_fma_f32 v[48:49], v[48:49], v[124:125], v[210:211]
	v_cvt_pk_bf16_f32 v208, v50, v51
	v_cvt_pk_bf16_f32 v209, v52, v53
	v_cvt_pk_bf16_f32 v210, v46, v47
	v_cvt_pk_bf16_f32 v211, v48, v49
	global_store_dwordx4 v[174:175], v[208:211], off offset:256
	s_mov_b32 s20, 0x48000
	s_mov_b32 s21, 0
	v_lshl_add_u64 v[174:175], v[172:173], 0, s[20:21]
	s_waitcnt vmcnt(14)
	v_lshlrev_b32_e32 v212, 16, v222
	v_and_b32_e32 v213, 0xffff0000, v222
	v_lshlrev_b32_e32 v248, 16, v224
	v_and_b32_e32 v249, 0xffff0000, v224
	v_lshlrev_b32_e32 v222, 16, v223
	v_and_b32_e32 v223, 0xffff0000, v223
	v_lshlrev_b32_e32 v224, 16, v225
	v_and_b32_e32 v225, 0xffff0000, v225
	v_pk_fma_f32 v[54:55], v[54:55], v[134:135], v[212:213]
	v_pk_fma_f32 v[42:43], v[42:43], v[130:131], v[248:249]
	v_pk_fma_f32 v[56:57], v[56:57], v[136:137], v[222:223]
	v_pk_fma_f32 v[44:45], v[44:45], v[132:133], v[224:225]
	v_cvt_pk_bf16_f32 v222, v54, v55
	v_cvt_pk_bf16_f32 v223, v56, v57
	v_cvt_pk_bf16_f32 v224, v42, v43
	v_cvt_pk_bf16_f32 v225, v44, v45
	global_store_dwordx4 v[174:175], v[222:225], off
	v_lshlrev_b32_e32 v212, 16, v226
	v_and_b32_e32 v213, 0xffff0000, v226
	v_lshlrev_b32_e32 v248, 16, v228
	v_and_b32_e32 v249, 0xffff0000, v228
	v_lshlrev_b32_e32 v226, 16, v227
	v_and_b32_e32 v227, 0xffff0000, v227
	v_lshlrev_b32_e32 v228, 16, v229
	v_and_b32_e32 v229, 0xffff0000, v229
	v_pk_fma_f32 v[38:39], v[38:39], v[126:127], v[212:213]
	v_pk_fma_f32 v[30:31], v[30:31], v[122:123], v[248:249]
	v_pk_fma_f32 v[40:41], v[40:41], v[128:129], v[226:227]
	v_pk_fma_f32 v[32:33], v[32:33], v[124:125], v[228:229]
	v_cvt_pk_bf16_f32 v226, v38, v39
	v_cvt_pk_bf16_f32 v227, v40, v41
	v_cvt_pk_bf16_f32 v228, v30, v31
	v_cvt_pk_bf16_f32 v229, v32, v33
	global_store_dwordx4 v[174:175], v[226:229], off offset:256
	s_mov_b32 s20, 0x50000
	s_mov_b32 s21, 0
	v_lshl_add_u64 v[174:175], v[172:173], 0, s[20:21]
	s_waitcnt vmcnt(14)
	v_lshlrev_b32_e32 v212, 16, v230
	v_and_b32_e32 v213, 0xffff0000, v230
	v_lshlrev_b32_e32 v248, 16, v232
	v_and_b32_e32 v249, 0xffff0000, v232
	v_lshlrev_b32_e32 v230, 16, v231
	v_and_b32_e32 v231, 0xffff0000, v231
	v_lshlrev_b32_e32 v232, 16, v233
	v_and_b32_e32 v233, 0xffff0000, v233
	v_pk_fma_f32 v[34:35], v[34:35], v[134:135], v[212:213]
	v_pk_fma_f32 v[26:27], v[26:27], v[130:131], v[248:249]
	v_pk_fma_f32 v[36:37], v[36:37], v[136:137], v[230:231]
	v_pk_fma_f32 v[28:29], v[28:29], v[132:133], v[232:233]
	v_cvt_pk_bf16_f32 v230, v34, v35
	v_cvt_pk_bf16_f32 v231, v36, v37
	v_cvt_pk_bf16_f32 v232, v26, v27
	v_cvt_pk_bf16_f32 v233, v28, v29
	global_store_dwordx4 v[174:175], v[230:233], off
	v_lshlrev_b32_e32 v212, 16, v234
	v_and_b32_e32 v213, 0xffff0000, v234
	v_lshlrev_b32_e32 v248, 16, v236
	v_and_b32_e32 v249, 0xffff0000, v236
	v_lshlrev_b32_e32 v234, 16, v235
	v_and_b32_e32 v235, 0xffff0000, v235
	v_lshlrev_b32_e32 v236, 16, v237
	v_and_b32_e32 v237, 0xffff0000, v237
	v_pk_fma_f32 v[18:19], v[18:19], v[126:127], v[212:213]
	v_pk_fma_f32 v[14:15], v[14:15], v[122:123], v[248:249]
	v_pk_fma_f32 v[20:21], v[20:21], v[128:129], v[234:235]
	v_pk_fma_f32 v[16:17], v[16:17], v[124:125], v[236:237]
	v_cvt_pk_bf16_f32 v234, v18, v19
	v_cvt_pk_bf16_f32 v235, v20, v21
	v_cvt_pk_bf16_f32 v236, v14, v15
	v_cvt_pk_bf16_f32 v237, v16, v17
	global_store_dwordx4 v[174:175], v[234:237], off offset:256
	s_mov_b32 s20, 0x58000
	s_mov_b32 s21, 0
	v_lshl_add_u64 v[174:175], v[172:173], 0, s[20:21]
	s_waitcnt vmcnt(14)
	v_lshlrev_b32_e32 v212, 16, v240
	v_and_b32_e32 v213, 0xffff0000, v240
	v_lshlrev_b32_e32 v248, 16, v242
	v_and_b32_e32 v249, 0xffff0000, v242
	v_lshlrev_b32_e32 v240, 16, v241
	v_and_b32_e32 v241, 0xffff0000, v241
	v_lshlrev_b32_e32 v242, 16, v243
	v_and_b32_e32 v243, 0xffff0000, v243
	v_pk_fma_f32 v[22:23], v[22:23], v[134:135], v[212:213]
	v_pk_fma_f32 v[10:11], v[10:11], v[130:131], v[248:249]
	v_pk_fma_f32 v[24:25], v[24:25], v[136:137], v[240:241]
	v_pk_fma_f32 v[12:13], v[12:13], v[132:133], v[242:243]
	v_cvt_pk_bf16_f32 v240, v22, v23
	v_cvt_pk_bf16_f32 v241, v24, v25
	v_cvt_pk_bf16_f32 v242, v10, v11
	v_cvt_pk_bf16_f32 v243, v12, v13
	global_store_dwordx4 v[174:175], v[240:243], off
	v_lshlrev_b32_e32 v212, 16, v244
	v_and_b32_e32 v213, 0xffff0000, v244
	v_lshlrev_b32_e32 v248, 16, v246
	v_and_b32_e32 v249, 0xffff0000, v246
	v_lshlrev_b32_e32 v244, 16, v245
	v_and_b32_e32 v245, 0xffff0000, v245
	v_lshlrev_b32_e32 v246, 16, v247
	v_and_b32_e32 v247, 0xffff0000, v247
	v_pk_fma_f32 v[6:7], v[6:7], v[126:127], v[212:213]
	v_pk_fma_f32 v[2:3], v[2:3], v[122:123], v[248:249]
	v_pk_fma_f32 v[8:9], v[8:9], v[128:129], v[244:245]
	v_pk_fma_f32 v[4:5], v[4:5], v[124:125], v[246:247]
	v_cvt_pk_bf16_f32 v244, v6, v7
	v_cvt_pk_bf16_f32 v245, v8, v9
	v_cvt_pk_bf16_f32 v246, v2, v3
	v_cvt_pk_bf16_f32 v247, v4, v5
	global_store_dwordx4 v[174:175], v[244:247], off offset:256
	s_andn2_b64 vcc, exec, s[0:1]
	s_mov_b64 s[0:1], -1
	s_movk_i32 s55, 0xf000
	s_mov_b32 s98, 1
	s_cbranch_vccnz .LBB0_71
	s_andn2_b64 vcc, exec, s[6:7]
	s_cbranch_vccnz .LBB0_70
	s_barrier
	s_branch .LBB0_70
.Lrelax_g2_w1:
	s_waitcnt vmcnt(24)
	s_branch .Lback_g2_w1
.Lrelax_g2_w2:
	s_waitcnt vmcnt(24)
	s_branch .Lback_g2_w2

.LBB0_105:
	s_add_u32 s22, s20, 0xfffc0080
	s_addc_u32 s23, s21, -1
	s_add_i32 s55, 0, 0x10000
	s_cmp_eq_u32 s49, 12
	s_cselect_b32 s25, s13, s23
	s_cselect_b32 s24, s45, s22
	s_cselect_b32 s23, s11, s48
	s_cselect_b32 s22, s46, s47
	s_add_i32 s58, 0, 0x14000
	v_add_u32_e32 v142, s55, v176
	v_add_u32_e32 v179, s58, v176
	ds_read_b128 v[130:133], v142
	ds_read_b128 v[134:137], v142 offset:1024
	ds_read_b128 v[138:141], v142 offset:2048
	ds_read_b128 v[142:145], v142 offset:3072
	ds_read_b128 v[146:149], v179
	ds_read_b128 v[154:157], v179 offset:1024
	ds_read_b128 v[172:175], v179 offset:2048
	ds_read_b128 v[180:183], v179 offset:3072
	v_lshl_add_u64 v[212:213], s[20:21], 0, v[170:171]
	s_add_i32 m0, s19, 0xc000
	ds_read_b128 v[184:187], v178
	ds_read_b128 v[188:191], v178 offset:1024
	ds_read_b128 v[192:195], v178 offset:2048
	ds_read_b128 v[196:199], v178 offset:3072
	ds_read_b128 v[200:203], v178 offset:4096
	ds_read_b128 v[204:207], v178 offset:5120
	ds_read_b128 v[208:211], v178 offset:6144
	ds_read_b128 v[222:225], v178 offset:7168
	s_cmp_lg_u32 s98, 0
	s_cbranch_scc1 .Lgc_skip_g3
	global_load_lds_dwordx4 v[212:213], off
	v_lshl_add_u64 v[212:213], s[20:21], 0, v[168:169]
	s_add_i32 m0, s19, 0xe000
	s_nop 0
	global_load_lds_dwordx4 v[212:213], off

.Lback_g3_w2:
	s_waitcnt lgkmcnt(0)
	s_barrier
	s_setprio 1
	s_waitcnt lgkmcnt(0)
	v_mfma_f32_16x16x32_bf16 v[62:65], v[130:133], v[184:187], v[62:65]
	v_mfma_f32_16x16x32_bf16 v[58:61], v[138:141], v[184:187], v[58:61]
	v_mfma_f32_16x16x32_bf16 v[46:49], v[130:133], v[192:195], v[46:49]
	v_mfma_f32_16x16x32_bf16 v[42:45], v[138:141], v[192:195], v[42:45]
	v_mfma_f32_16x16x32_bf16 v[30:33], v[130:133], v[200:203], v[30:33]
	v_mfma_f32_16x16x32_bf16 v[26:29], v[138:141], v[200:203], v[26:29]
	v_mfma_f32_16x16x32_bf16 v[14:17], v[130:133], v[208:211], v[14:17]
	v_mfma_f32_16x16x32_bf16 v[10:13], v[138:141], v[208:211], v[10:13]
	v_mfma_f32_16x16x32_bf16 v[62:65], v[134:137], v[188:191], v[62:65]
	v_mfma_f32_16x16x32_bf16 v[58:61], v[142:145], v[188:191], v[58:61]
	v_mfma_f32_16x16x32_bf16 v[46:49], v[134:137], v[196:199], v[46:49]
	v_mfma_f32_16x16x32_bf16 v[42:45], v[142:145], v[196:199], v[42:45]
	v_mfma_f32_16x16x32_bf16 v[30:33], v[134:137], v[204:207], v[30:33]
	v_mfma_f32_16x16x32_bf16 v[26:29], v[142:145], v[204:207], v[26:29]
	v_mfma_f32_16x16x32_bf16 v[14:17], v[134:137], v[222:225], v[14:17]
	v_mfma_f32_16x16x32_bf16 v[10:13], v[142:145], v[222:225], v[10:13]
	s_setprio 0
	s_setprio 1
	v_mfma_f32_16x16x32_bf16 v[54:57], v[146:149], v[184:187], v[54:57]
	v_mfma_f32_16x16x32_bf16 v[50:53], v[172:175], v[184:187], v[50:53]
	v_mfma_f32_16x16x32_bf16 v[38:41], v[146:149], v[192:195], v[38:41]
	v_mfma_f32_16x16x32_bf16 v[34:37], v[172:175], v[192:195], v[34:37]
	v_mfma_f32_16x16x32_bf16 v[22:25], v[146:149], v[200:203], v[22:25]
	v_mfma_f32_16x16x32_bf16 v[18:21], v[172:175], v[200:203], v[18:21]
	v_mfma_f32_16x16x32_bf16 v[6:9], v[146:149], v[208:211], v[6:9]
	v_mfma_f32_16x16x32_bf16 v[2:5], v[172:175], v[208:211], v[2:5]
	v_mfma_f32_16x16x32_bf16 v[54:57], v[154:157], v[188:191], v[54:57]
	v_mfma_f32_16x16x32_bf16 v[50:53], v[180:183], v[188:191], v[50:53]
	v_mfma_f32_16x16x32_bf16 v[38:41], v[154:157], v[196:199], v[38:41]
	v_mfma_f32_16x16x32_bf16 v[34:37], v[180:183], v[196:199], v[34:37]
	v_mfma_f32_16x16x32_bf16 v[22:25], v[154:157], v[204:207], v[22:25]
	v_mfma_f32_16x16x32_bf16 v[18:21], v[180:183], v[204:207], v[18:21]
	v_mfma_f32_16x16x32_bf16 v[6:9], v[154:157], v[222:225], v[6:9]
	v_mfma_f32_16x16x32_bf16 v[2:5], v[180:183], v[222:225], v[2:5]
	s_setprio 0
	s_barrier
	s_add_i32 s55, 0, 0x18000
	s_add_i32 s56, 0, 0x1c000
	v_add_u32_e32 v142, s55, v176
	v_add_u32_e32 v179, s56, v176
	ds_read_b128 v[130:133], v142
	ds_read_b128 v[134:137], v142 offset:1024
	ds_read_b128 v[138:141], v142 offset:2048
	ds_read_b128 v[142:145], v142 offset:3072
	ds_read_b128 v[146:149], v179
	ds_read_b128 v[154:157], v179 offset:1024
	ds_read_b128 v[172:175], v179 offset:2048
	ds_read_b128 v[180:183], v179 offset:3072
	s_add_u32 s24, s24, 0x40000
	s_addc_u32 s25, s25, 0
	s_mov_b32 m0, s31
	v_lshl_add_u64 v[232:233], s[24:25], 0, v[162:163]
	ds_read_b128 v[184:187], v178 offset:32768
	ds_read_b128 v[188:191], v178 offset:33792
	ds_read_b128 v[192:195], v178 offset:34816
	ds_read_b128 v[196:199], v178 offset:35840
	ds_read_b128 v[200:203], v178 offset:36864
	ds_read_b128 v[204:207], v178 offset:37888
	ds_read_b128 v[208:211], v178 offset:38912
	ds_read_b128 v[222:225], v178 offset:39936
	global_load_lds_dwordx4 v[232:233], off
	v_lshl_add_u64 v[232:233], s[24:25], 0, v[164:165]
	s_mov_b32 m0, s37
	s_nop 0
	global_load_lds_dwordx4 v[232:233], off
	s_cmp_lg_u32 s98, 0
	s_cbranch_scc1 .Lrelax_g3_w3
	s_waitcnt vmcnt(8)
.Lback_g3_w3:
	s_waitcnt lgkmcnt(0)
	s_barrier
	s_setprio 1
	s_waitcnt lgkmcnt(0)
	v_mfma_f32_16x16x32_bf16 v[126:129], v[130:133], v[184:187], v[126:129]
	v_mfma_f32_16x16x32_bf16 v[122:125], v[138:141], v[184:187], v[122:125]
	v_mfma_f32_16x16x32_bf16 v[110:113], v[130:133], v[192:195], v[110:113]
	v_mfma_f32_16x16x32_bf16 v[106:109], v[138:141], v[192:195], v[106:109]
	v_mfma_f32_16x16x32_bf16 v[94:97], v[130:133], v[200:203], v[94:97]
	v_mfma_f32_16x16x32_bf16 v[90:93], v[138:141], v[200:203], v[90:93]
	v_mfma_f32_16x16x32_bf16 v[78:81], v[130:133], v[208:211], v[78:81]
	v_mfma_f32_16x16x32_bf16 v[74:77], v[138:141], v[208:211], v[74:77]
	v_mfma_f32_16x16x32_bf16 v[126:129], v[134:137], v[188:191], v[126:129]
	v_mfma_f32_16x16x32_bf16 v[122:125], v[142:145], v[188:191], v[122:125]
	v_mfma_f32_16x16x32_bf16 v[110:113], v[134:137], v[196:199], v[110:113]
	v_mfma_f32_16x16x32_bf16 v[106:109], v[142:145], v[196:199], v[106:109]
	v_mfma_f32_16x16x32_bf16 v[94:97], v[134:137], v[204:207], v[94:97]
	v_mfma_f32_16x16x32_bf16 v[90:93], v[142:145], v[204:207], v[90:93]
	v_mfma_f32_16x16x32_bf16 v[78:81], v[134:137], v[222:225], v[78:81]
	v_mfma_f32_16x16x32_bf16 v[74:77], v[142:145], v[222:225], v[74:77]
	s_setprio 0
	s_setprio 1
	v_mfma_f32_16x16x32_bf16 v[118:121], v[146:149], v[184:187], v[118:121]
	v_mfma_f32_16x16x32_bf16 v[114:117], v[172:175], v[184:187], v[114:117]
	v_mfma_f32_16x16x32_bf16 v[102:105], v[146:149], v[192:195], v[102:105]
	v_mfma_f32_16x16x32_bf16 v[98:101], v[172:175], v[192:195], v[98:101]
	v_mfma_f32_16x16x32_bf16 v[86:89], v[146:149], v[200:203], v[86:89]
	v_mfma_f32_16x16x32_bf16 v[82:85], v[172:175], v[200:203], v[82:85]
	v_mfma_f32_16x16x32_bf16 v[70:73], v[146:149], v[208:211], v[70:73]
	v_mfma_f32_16x16x32_bf16 v[66:69], v[172:175], v[208:211], v[66:69]
	v_mfma_f32_16x16x32_bf16 v[118:121], v[154:157], v[188:191], v[118:121]
	v_mfma_f32_16x16x32_bf16 v[114:117], v[180:183], v[188:191], v[114:117]
	v_mfma_f32_16x16x32_bf16 v[102:105], v[154:157], v[196:199], v[102:105]
	v_mfma_f32_16x16x32_bf16 v[98:101], v[180:183], v[196:199], v[98:101]
	v_mfma_f32_16x16x32_bf16 v[86:89], v[154:157], v[204:207], v[86:89]
	v_mfma_f32_16x16x32_bf16 v[82:85], v[180:183], v[204:207], v[82:85]
	v_mfma_f32_16x16x32_bf16 v[70:73], v[154:157], v[222:225], v[70:73]
	v_mfma_f32_16x16x32_bf16 v[66:69], v[180:183], v[222:225], v[66:69]
	s_setprio 0
	s_barrier
	s_add_i32 s24, s55, s29
	v_lshl_add_u64 v[212:213], v[212:213], 0, s[96:97]
	s_mov_b32 m0, s24
	ds_read_b128 v[184:187], v178 offset:49152
	ds_read_b128 v[188:191], v178 offset:50176
	ds_read_b128 v[192:195], v178 offset:51200
	ds_read_b128 v[196:199], v178 offset:52224
	ds_read_b128 v[200:203], v178 offset:53248
	ds_read_b128 v[204:207], v178 offset:54272
	ds_read_b128 v[208:211], v178 offset:55296
	ds_read_b128 v[222:225], v178 offset:56320
	global_load_lds_dwordx4 v[212:213], off
	s_add_i32 m0, s24, 0x2000
	s_add_u32 s22, s22, 0x40080
	v_lshl_add_u64 v[212:213], v[226:227], 0, s[96:97]
	s_addc_u32 s23, s23, 0
	s_add_i32 s24, s56, s29
	global_load_lds_dwordx4 v[212:213], off
	v_lshl_add_u64 v[212:213], s[22:23], 0, v[0:1]
	s_mov_b32 m0, s24
	s_nop 0
	global_load_lds_dwordx4 v[212:213], off
	v_lshl_add_u64 v[212:213], s[22:23], 0, v[166:167]
	s_add_i32 m0, s24, 0x2000
	s_nop 0
	global_load_lds_dwordx4 v[212:213], off
	v_lshl_add_u64 v[212:213], v[228:229], 0, s[96:97]
	s_mov_b32 m0, s40
	s_nop 0
	global_load_lds_dwordx4 v[212:213], off
	v_lshl_add_u64 v[212:213], v[230:231], 0, s[96:97]
	s_mov_b32 m0, s41
	s_nop 0
	global_load_lds_dwordx4 v[212:213], off
	s_waitcnt vmcnt(8)
	s_waitcnt lgkmcnt(0)
	s_barrier
	s_setprio 1
	s_waitcnt lgkmcnt(0)
	v_mfma_f32_16x16x32_bf16 v[62:65], v[130:133], v[184:187], v[62:65]
	v_mfma_f32_16x16x32_bf16 v[58:61], v[138:141], v[184:187], v[58:61]
	v_mfma_f32_16x16x32_bf16 v[46:49], v[130:133], v[192:195], v[46:49]
	v_mfma_f32_16x16x32_bf16 v[42:45], v[138:141], v[192:195], v[42:45]
	v_mfma_f32_16x16x32_bf16 v[30:33], v[130:133], v[200:203], v[30:33]
	v_mfma_f32_16x16x32_bf16 v[26:29], v[138:141], v[200:203], v[26:29]
	v_mfma_f32_16x16x32_bf16 v[14:17], v[130:133], v[208:211], v[14:17]
	v_mfma_f32_16x16x32_bf16 v[10:13], v[138:141], v[208:211], v[10:13]
	v_mfma_f32_16x16x32_bf16 v[62:65], v[134:137], v[188:191], v[62:65]
	v_mfma_f32_16x16x32_bf16 v[58:61], v[142:145], v[188:191], v[58:61]
	v_mfma_f32_16x16x32_bf16 v[46:49], v[134:137], v[196:199], v[46:49]
	v_mfma_f32_16x16x32_bf16 v[42:45], v[142:145], v[196:199], v[42:45]
	v_mfma_f32_16x16x32_bf16 v[30:33], v[134:137], v[204:207], v[30:33]
	v_mfma_f32_16x16x32_bf16 v[26:29], v[142:145], v[204:207], v[26:29]
	v_mfma_f32_16x16x32_bf16 v[14:17], v[134:137], v[222:225], v[14:17]
	v_mfma_f32_16x16x32_bf16 v[10:13], v[142:145], v[222:225], v[10:13]
	s_setprio 0
	s_setprio 1
	v_mfma_f32_16x16x32_bf16 v[54:57], v[146:149], v[184:187], v[54:57]
	v_mfma_f32_16x16x32_bf16 v[50:53], v[172:175], v[184:187], v[50:53]
	v_mfma_f32_16x16x32_bf16 v[38:41], v[146:149], v[192:195], v[38:41]
	v_mfma_f32_16x16x32_bf16 v[34:37], v[172:175], v[192:195], v[34:37]
	v_mfma_f32_16x16x32_bf16 v[22:25], v[146:149], v[200:203], v[22:25]
	v_mfma_f32_16x16x32_bf16 v[18:21], v[172:175], v[200:203], v[18:21]
	v_mfma_f32_16x16x32_bf16 v[6:9], v[146:149], v[208:211], v[6:9]
	v_mfma_f32_16x16x32_bf16 v[2:5], v[172:175], v[208:211], v[2:5]
	v_mfma_f32_16x16x32_bf16 v[54:57], v[154:157], v[188:191], v[54:57]
	v_mfma_f32_16x16x32_bf16 v[50:53], v[180:183], v[188:191], v[50:53]
	v_mfma_f32_16x16x32_bf16 v[38:41], v[154:157], v[196:199], v[38:41]
	v_mfma_f32_16x16x32_bf16 v[34:37], v[180:183], v[196:199], v[34:37]
	v_mfma_f32_16x16x32_bf16 v[22:25], v[154:157], v[204:207], v[22:25]
	v_mfma_f32_16x16x32_bf16 v[18:21], v[180:183], v[204:207], v[18:21]
	v_mfma_f32_16x16x32_bf16 v[6:9], v[154:157], v[222:225], v[6:9]
	v_mfma_f32_16x16x32_bf16 v[2:5], v[180:183], v[222:225], v[2:5]
	s_setprio 0
	s_barrier
	s_add_i32 s49, s49, 2
	s_add_u32 s47, s47, 0x100
	s_addc_u32 s48, s48, 0
	s_add_u32 s20, s20, 0x100
	s_addc_u32 s21, s21, 0
	s_cmp_gt_u32 s49, 13
	s_cbranch_scc0 .LBB0_105
	s_add_u32 s20, s45, 0x40080
	s_addc_u32 s21, s13, 0
	s_and_b64 vcc, exec, s[8:9]
	s_movk_i32 s46, 0xd000
	s_movk_i32 s47, 0xec00
	s_cbranch_vccz .LBB0_108
	s_barrier
.LBB0_108:
	v_lshl_add_u64 v[212:213], s[20:21], 0, v[170:171]
	s_add_i32 m0, s19, 0xc000
	s_nop 0
	global_load_lds_dwordx4 v[212:213], off
	v_lshl_add_u64 v[212:213], s[20:21], 0, v[168:169]
	s_add_i32 m0, s19, 0xe000
	s_nop 0
	global_load_lds_dwordx4 v[212:213], off
	s_ashr_i32 s11, s18, 4
	v_lshl_add_u32 v174, s18, 8, v159
	v_lshl_or_b32 v172, s44, 8, v177
	s_mul_hi_i32 s13, s11, 0x6000
	s_mulk_i32 s11, 0x6000
	v_ashrrev_i32_e32 v175, 31, v174
	s_add_u32 s20, s38, s11
	v_ashrrev_i32_e32 v173, 31, v172
	v_lshlrev_b64 v[134:135], 10, v[174:175]
	v_readlane_b32 s64, v253, 62
	s_addc_u32 s21, s39, s13
	v_lshl_add_u64 v[140:141], v[134:135], 0, v[172:173]
	v_readlane_b32 s65, v253, 63
	v_lshl_add_u64 v[138:139], v[172:173], 2, s[20:21]
	flat_load_dwordx4 v[130:133], v[138:139]
	v_lshl_add_u64 v[180:181], v[140:141], 2, s[64:65]
	global_load_dwordx4 v[146:149], v[180:181], off
	global_load_dwordx4 v[154:157], v[180:181], off offset:16
	flat_load_dwordx4 v[134:137], v[138:139] offset:16
	v_lshl_add_u64 v[182:183], v[140:141], 1, s[4:5]
	flat_load_dwordx4 v[142:145], v[138:139] offset:512
	s_nop 0
	flat_load_dwordx4 v[138:141], v[138:139] offset:528
	s_andn2_b64 vcc, exec, s[0:1]
	s_mov_b64 s[0:1], -1
	s_movk_i32 s55, 0xf000
	v_readlane_b32 s66, v254, 0
	v_readlane_b32 s67, v254, 1
	v_readlane_b32 s68, v254, 2
	v_readlane_b32 s69, v254, 3
	v_readlane_b32 s70, v254, 4
	v_readlane_b32 s71, v254, 5
	v_readlane_b32 s72, v254, 6
	v_readlane_b32 s73, v254, 7
	v_readlane_b32 s74, v254, 8
	v_readlane_b32 s75, v254, 9
	v_readlane_b32 s76, v254, 10
	v_readlane_b32 s77, v254, 11
	v_readlane_b32 s78, v254, 12
	v_readlane_b32 s79, v254, 13
	s_waitcnt vmcnt(0) lgkmcnt(0)
	v_pk_fma_f32 v[126:127], v[126:127], v[130:131], v[146:147]
	v_pk_fma_f32 v[128:129], v[128:129], v[132:133], v[148:149]
	v_pk_fma_f32 v[146:147], v[124:125], v[136:137], v[156:157]
	v_pk_fma_f32 v[124:125], v[122:123], v[134:135], v[154:155]
	v_cvt_pk_bf16_f32 v122, v126, v127
	v_cvt_pk_bf16_f32 v123, v128, v129
	s_nop 0
	v_cvt_pk_bf16_f32 v124, v124, v125
	v_cvt_pk_bf16_f32 v125, v146, v147
	flat_store_dwordx4 v[182:183], v[122:125]
	global_load_dwordx4 v[122:125], v[180:181], off offset:512
	s_nop 0
	global_load_dwordx4 v[126:129], v[180:181], off offset:528
	v_or_b32_e32 v146, 16, v174
	v_ashrrev_i32_e32 v147, 31, v146
	v_lshlrev_b64 v[146:147], 10, v[146:147]
	v_lshl_add_u64 v[146:147], v[146:147], 0, v[172:173]
	v_lshl_add_u64 v[148:149], v[146:147], 2, s[64:65]
	s_waitcnt vmcnt(0)
	v_pk_fma_f32 v[118:119], v[118:119], v[142:143], v[122:123]
	v_pk_fma_f32 v[122:123], v[116:117], v[140:141], v[128:129]
	v_pk_fma_f32 v[116:117], v[114:115], v[138:139], v[126:127]
	v_pk_fma_f32 v[120:121], v[120:121], v[144:145], v[124:125]
	v_cvt_pk_bf16_f32 v114, v118, v119
	s_nop 0
	v_cvt_pk_bf16_f32 v115, v120, v121
	v_cvt_pk_bf16_f32 v116, v116, v117
	v_cvt_pk_bf16_f32 v117, v122, v123
	flat_store_dwordx4 v[182:183], v[114:117] offset:256
	global_load_dwordx4 v[114:117], v[148:149], off
	s_nop 0
	global_load_dwordx4 v[118:121], v[148:149], off offset:16
	v_lshl_add_u64 v[122:123], v[146:147], 1, s[4:5]
	s_waitcnt vmcnt(0)
	v_pk_fma_f32 v[110:111], v[110:111], v[130:131], v[114:115]
	v_pk_fma_f32 v[114:115], v[108:109], v[136:137], v[120:121]
	v_pk_fma_f32 v[108:109], v[106:107], v[134:135], v[118:119]
	v_pk_fma_f32 v[112:113], v[112:113], v[132:133], v[116:117]
	v_cvt_pk_bf16_f32 v106, v110, v111
	s_nop 0
	v_cvt_pk_bf16_f32 v107, v112, v113
	v_cvt_pk_bf16_f32 v108, v108, v109
	v_cvt_pk_bf16_f32 v109, v114, v115
	flat_store_dwordx4 v[122:123], v[106:109]
	global_load_dwordx4 v[106:109], v[148:149], off offset:512
	s_nop 0
	global_load_dwordx4 v[110:113], v[148:149], off offset:528
	v_or_b32_e32 v114, 32, v174
	v_ashrrev_i32_e32 v115, 31, v114
	v_lshlrev_b64 v[114:115], 10, v[114:115]
	v_lshl_add_u64 v[114:115], v[114:115], 0, v[172:173]
	v_lshl_add_u64 v[116:117], v[114:115], 2, s[64:65]
	s_waitcnt vmcnt(0)
	v_pk_fma_f32 v[102:103], v[102:103], v[142:143], v[106:107]
	v_pk_fma_f32 v[106:107], v[100:101], v[140:141], v[112:113]
	v_pk_fma_f32 v[100:101], v[98:99], v[138:139], v[110:111]
	v_pk_fma_f32 v[104:105], v[104:105], v[144:145], v[108:109]
	v_cvt_pk_bf16_f32 v98, v102, v103
	s_nop 0
	v_cvt_pk_bf16_f32 v99, v104, v105
	v_cvt_pk_bf16_f32 v100, v100, v101
	v_cvt_pk_bf16_f32 v101, v106, v107
	flat_store_dwordx4 v[122:123], v[98:101] offset:256
	global_load_dwordx4 v[98:101], v[116:117], off
	global_load_dwordx4 v[102:105], v[116:117], off offset:16
	v_lshl_add_u64 v[106:107], v[114:115], 1, s[4:5]
	s_waitcnt vmcnt(0)
	v_pk_fma_f32 v[94:95], v[94:95], v[130:131], v[98:99]
	v_pk_fma_f32 v[98:99], v[92:93], v[136:137], v[104:105]
	v_pk_fma_f32 v[92:93], v[90:91], v[134:135], v[102:103]
	v_pk_fma_f32 v[96:97], v[96:97], v[132:133], v[100:101]
	v_cvt_pk_bf16_f32 v90, v94, v95
	s_nop 0
	v_cvt_pk_bf16_f32 v91, v96, v97
	v_cvt_pk_bf16_f32 v92, v92, v93
	v_cvt_pk_bf16_f32 v93, v98, v99
	flat_store_dwordx4 v[106:107], v[90:93]
	global_load_dwordx4 v[90:93], v[116:117], off offset:512
	s_nop 0
	global_load_dwordx4 v[94:97], v[116:117], off offset:528
	v_or_b32_e32 v98, 48, v174
	v_ashrrev_i32_e32 v99, 31, v98
	v_lshlrev_b64 v[98:99], 10, v[98:99]
	v_lshl_add_u64 v[98:99], v[98:99], 0, v[172:173]
	v_lshl_add_u64 v[100:101], v[98:99], 2, s[64:65]
	s_waitcnt vmcnt(0)
	v_pk_fma_f32 v[86:87], v[86:87], v[142:143], v[90:91]
	v_pk_fma_f32 v[90:91], v[84:85], v[140:141], v[96:97]
	v_pk_fma_f32 v[84:85], v[82:83], v[138:139], v[94:95]
	v_pk_fma_f32 v[88:89], v[88:89], v[144:145], v[92:93]
	v_cvt_pk_bf16_f32 v82, v86, v87
	s_nop 0
	v_cvt_pk_bf16_f32 v83, v88, v89
	v_cvt_pk_bf16_f32 v84, v84, v85
	v_cvt_pk_bf16_f32 v85, v90, v91
	flat_store_dwordx4 v[106:107], v[82:85] offset:256
	global_load_dwordx4 v[82:85], v[100:101], off
	s_nop 0
	global_load_dwordx4 v[86:89], v[100:101], off offset:16
	v_lshl_add_u64 v[90:91], v[98:99], 1, s[4:5]
	s_waitcnt vmcnt(0)
	v_pk_fma_f32 v[78:79], v[78:79], v[130:131], v[82:83]
	v_pk_fma_f32 v[82:83], v[76:77], v[136:137], v[88:89]
	v_pk_fma_f32 v[76:77], v[74:75], v[134:135], v[86:87]
	v_pk_fma_f32 v[80:81], v[80:81], v[132:133], v[84:85]
	v_cvt_pk_bf16_f32 v74, v78, v79
	s_nop 0
	v_cvt_pk_bf16_f32 v75, v80, v81
	v_cvt_pk_bf16_f32 v76, v76, v77
	v_cvt_pk_bf16_f32 v77, v82, v83
	flat_store_dwordx4 v[90:91], v[74:77]
	global_load_dwordx4 v[74:77], v[100:101], off offset:512
	s_nop 0
	global_load_dwordx4 v[78:81], v[100:101], off offset:528
	v_add_u32_e32 v82, 0x80, v174
	v_ashrrev_i32_e32 v83, 31, v82
	v_lshlrev_b64 v[82:83], 10, v[82:83]
	v_lshl_add_u64 v[82:83], v[82:83], 0, v[172:173]
	v_lshl_add_u64 v[84:85], v[82:83], 2, s[64:65]
	s_waitcnt vmcnt(0)
	v_pk_fma_f32 v[70:71], v[70:71], v[142:143], v[74:75]
	v_pk_fma_f32 v[74:75], v[68:69], v[140:141], v[80:81]
	v_pk_fma_f32 v[68:69], v[66:67], v[138:139], v[78:79]
	v_pk_fma_f32 v[72:73], v[72:73], v[144:145], v[76:77]
	v_cvt_pk_bf16_f32 v66, v70, v71
	s_nop 0
	v_cvt_pk_bf16_f32 v67, v72, v73
	v_cvt_pk_bf16_f32 v68, v68, v69
	v_cvt_pk_bf16_f32 v69, v74, v75
	flat_store_dwordx4 v[90:91], v[66:69] offset:256
	global_load_dwordx4 v[66:69], v[84:85], off
	global_load_dwordx4 v[70:73], v[84:85], off offset:16
	v_lshl_add_u64 v[74:75], v[82:83], 1, s[4:5]
	s_waitcnt vmcnt(0)
	v_pk_fma_f32 v[62:63], v[62:63], v[130:131], v[66:67]
	v_pk_fma_f32 v[66:67], v[60:61], v[136:137], v[72:73]
	v_pk_fma_f32 v[60:61], v[58:59], v[134:135], v[70:71]
	v_pk_fma_f32 v[64:65], v[64:65], v[132:133], v[68:69]
	v_cvt_pk_bf16_f32 v58, v62, v63
	s_nop 0
	v_cvt_pk_bf16_f32 v59, v64, v65
	v_cvt_pk_bf16_f32 v60, v60, v61
	v_cvt_pk_bf16_f32 v61, v66, v67
	flat_store_dwordx4 v[74:75], v[58:61]
	global_load_dwordx4 v[58:61], v[84:85], off offset:512
	s_nop 0
	global_load_dwordx4 v[62:65], v[84:85], off offset:528
	v_add_u32_e32 v66, 0x90, v174
	v_ashrrev_i32_e32 v67, 31, v66
	v_lshlrev_b64 v[66:67], 10, v[66:67]
	v_lshl_add_u64 v[66:67], v[66:67], 0, v[172:173]
	v_lshl_add_u64 v[68:69], v[66:67], 2, s[64:65]
	s_waitcnt vmcnt(0)
	v_pk_fma_f32 v[54:55], v[54:55], v[142:143], v[58:59]
	v_pk_fma_f32 v[58:59], v[52:53], v[140:141], v[64:65]
	v_pk_fma_f32 v[52:53], v[50:51], v[138:139], v[62:63]
	v_pk_fma_f32 v[56:57], v[56:57], v[144:145], v[60:61]
	v_cvt_pk_bf16_f32 v50, v54, v55
	s_nop 0
	v_cvt_pk_bf16_f32 v51, v56, v57
	v_cvt_pk_bf16_f32 v52, v52, v53
	v_cvt_pk_bf16_f32 v53, v58, v59
	flat_store_dwordx4 v[74:75], v[50:53] offset:256
	global_load_dwordx4 v[50:53], v[68:69], off
	s_nop 0
	global_load_dwordx4 v[54:57], v[68:69], off offset:16
	v_lshl_add_u64 v[58:59], v[66:67], 1, s[4:5]
	s_waitcnt vmcnt(0)
	v_pk_fma_f32 v[46:47], v[46:47], v[130:131], v[50:51]
	v_pk_fma_f32 v[50:51], v[44:45], v[136:137], v[56:57]
	v_pk_fma_f32 v[44:45], v[42:43], v[134:135], v[54:55]
	v_pk_fma_f32 v[48:49], v[48:49], v[132:133], v[52:53]
	v_cvt_pk_bf16_f32 v42, v46, v47
	s_nop 0
	v_cvt_pk_bf16_f32 v43, v48, v49
	v_cvt_pk_bf16_f32 v44, v44, v45
	v_cvt_pk_bf16_f32 v45, v50, v51
	flat_store_dwordx4 v[58:59], v[42:45]
	global_load_dwordx4 v[42:45], v[68:69], off offset:512
	s_nop 0
	global_load_dwordx4 v[46:49], v[68:69], off offset:528
	v_add_u32_e32 v50, 0xa0, v174
	v_ashrrev_i32_e32 v51, 31, v50
	v_lshlrev_b64 v[50:51], 10, v[50:51]
	v_lshl_add_u64 v[50:51], v[50:51], 0, v[172:173]
	v_lshl_add_u64 v[52:53], v[50:51], 2, s[64:65]
	s_waitcnt vmcnt(0)
	v_pk_fma_f32 v[38:39], v[38:39], v[142:143], v[42:43]
	v_pk_fma_f32 v[42:43], v[36:37], v[140:141], v[48:49]
	v_pk_fma_f32 v[36:37], v[34:35], v[138:139], v[46:47]
	v_pk_fma_f32 v[40:41], v[40:41], v[144:145], v[44:45]
	v_cvt_pk_bf16_f32 v34, v38, v39
	s_nop 0
	v_cvt_pk_bf16_f32 v35, v40, v41
	v_cvt_pk_bf16_f32 v36, v36, v37
	v_cvt_pk_bf16_f32 v37, v42, v43
	flat_store_dwordx4 v[58:59], v[34:37] offset:256
	global_load_dwordx4 v[34:37], v[52:53], off
	global_load_dwordx4 v[38:41], v[52:53], off offset:16
	v_lshl_add_u64 v[42:43], v[50:51], 1, s[4:5]
	s_waitcnt vmcnt(0)
	v_pk_fma_f32 v[30:31], v[30:31], v[130:131], v[34:35]
	v_pk_fma_f32 v[34:35], v[28:29], v[136:137], v[40:41]
	v_pk_fma_f32 v[28:29], v[26:27], v[134:135], v[38:39]
	v_pk_fma_f32 v[32:33], v[32:33], v[132:133], v[36:37]
	v_cvt_pk_bf16_f32 v26, v30, v31
	s_nop 0
	v_cvt_pk_bf16_f32 v27, v32, v33
	v_cvt_pk_bf16_f32 v28, v28, v29
	v_cvt_pk_bf16_f32 v29, v34, v35
	flat_store_dwordx4 v[42:43], v[26:29]
	global_load_dwordx4 v[26:29], v[52:53], off offset:512
	s_nop 0
	global_load_dwordx4 v[30:33], v[52:53], off offset:528
	v_add_u32_e32 v34, 0xb0, v174
	v_ashrrev_i32_e32 v35, 31, v34
	v_lshlrev_b64 v[34:35], 10, v[34:35]
	v_lshl_add_u64 v[34:35], v[34:35], 0, v[172:173]
	v_lshl_add_u64 v[36:37], v[34:35], 2, s[64:65]
	s_waitcnt vmcnt(0)
	v_pk_fma_f32 v[22:23], v[22:23], v[142:143], v[26:27]
	v_pk_fma_f32 v[26:27], v[20:21], v[140:141], v[32:33]
	v_pk_fma_f32 v[20:21], v[18:19], v[138:139], v[30:31]
	v_pk_fma_f32 v[24:25], v[24:25], v[144:145], v[28:29]
	v_cvt_pk_bf16_f32 v18, v22, v23
	s_nop 0
	v_cvt_pk_bf16_f32 v19, v24, v25
	v_cvt_pk_bf16_f32 v20, v20, v21
	v_cvt_pk_bf16_f32 v21, v26, v27
	flat_store_dwordx4 v[42:43], v[18:21] offset:256
	global_load_dwordx4 v[18:21], v[36:37], off
	s_nop 0
	global_load_dwordx4 v[22:25], v[36:37], off offset:16
	v_lshl_add_u64 v[26:27], v[34:35], 1, s[4:5]
	s_waitcnt vmcnt(0)
	v_pk_fma_f32 v[14:15], v[14:15], v[130:131], v[18:19]
	v_pk_fma_f32 v[18:19], v[12:13], v[136:137], v[24:25]
	v_pk_fma_f32 v[12:13], v[10:11], v[134:135], v[22:23]
	v_pk_fma_f32 v[16:17], v[16:17], v[132:133], v[20:21]
	v_cvt_pk_bf16_f32 v10, v14, v15
	s_nop 0
	v_cvt_pk_bf16_f32 v11, v16, v17
	v_cvt_pk_bf16_f32 v12, v12, v13
	v_cvt_pk_bf16_f32 v13, v18, v19
	flat_store_dwordx4 v[26:27], v[10:13]
	global_load_dwordx4 v[10:13], v[36:37], off offset:512
	s_nop 0
	global_load_dwordx4 v[14:17], v[36:37], off offset:528
	s_waitcnt vmcnt(0)
	v_pk_fma_f32 v[6:7], v[6:7], v[142:143], v[10:11]
	v_pk_fma_f32 v[10:11], v[4:5], v[140:141], v[16:17]
	v_pk_fma_f32 v[4:5], v[2:3], v[138:139], v[14:15]
	v_pk_fma_f32 v[8:9], v[8:9], v[144:145], v[12:13]
	v_cvt_pk_bf16_f32 v2, v6, v7
	s_nop 0
	v_cvt_pk_bf16_f32 v3, v8, v9
	v_cvt_pk_bf16_f32 v4, v4, v5
	v_cvt_pk_bf16_f32 v5, v10, v11
	flat_store_dwordx4 v[26:27], v[2:5] offset:256
	s_mov_b32 s98, 1
	s_cbranch_vccnz .LBB0_97
	s_andn2_b64 vcc, exec, s[6:7]
	s_cbranch_vccnz .LBB0_96
	s_barrier
	s_branch .LBB0_96
.Lrelax_g3_w1:
	s_waitcnt vmcnt(24)
	s_branch .Lback_g3_w1
.Lrelax_g3_w2:
	s_waitcnt vmcnt(24)
	s_branch .Lback_g3_w2

.LBB0_353:
	s_add_u32 s22, s20, 0xfffc0080
	s_addc_u32 s23, s21, -1
	s_add_i32 s55, 0, 0x10000
	s_cmp_eq_u32 s49, 12
	s_cselect_b32 s25, s13, s23
	s_cselect_b32 s24, s45, s22
	v_add_u32_e32 v140, s55, v143
	s_cselect_b32 s23, s11, s48
	s_cselect_b32 s22, s46, s47
	s_add_i32 s58, 0, 0x14000
	ds_read_b128 v[162:165], v140
	ds_read_b128 v[166:169], v140 offset:1024
	ds_read_b128 v[170:173], v140 offset:2048
	ds_read_b128 v[174:177], v140 offset:3072
	v_add_u32_e32 v140, s58, v143
	ds_read_b128 v[178:181], v140
	ds_read_b128 v[182:185], v140 offset:1024
	ds_read_b128 v[186:189], v140 offset:2048
	ds_read_b128 v[190:193], v140 offset:3072
	v_lshl_add_u64 v[140:141], s[20:21], 0, v[138:139]
	s_add_i32 m0, s19, 0xc000
	ds_read_b128 v[194:197], v145
	ds_read_b128 v[198:201], v145 offset:1024
	ds_read_b128 v[202:205], v145 offset:2048
	ds_read_b128 v[206:209], v145 offset:3072
	ds_read_b128 v[210:213], v145 offset:4096
	ds_read_b128 v[222:225], v145 offset:5120
	ds_read_b128 v[226:229], v145 offset:6144
	ds_read_b128 v[230:233], v145 offset:7168
	s_cmp_lg_u32 s98, 0
	s_cbranch_scc1 .Lgc_skip_g4
	global_load_lds_dwordx4 v[140:141], off
	v_lshl_add_u64 v[140:141], s[20:21], 0, v[136:137]
	s_add_i32 m0, s19, 0xe000
	s_nop 0
	global_load_lds_dwordx4 v[140:141], off

.Lback_g4_w2:
	s_waitcnt lgkmcnt(0)
	s_barrier
	s_setprio 1
	s_waitcnt lgkmcnt(0)
	v_mfma_f32_16x16x32_bf16 v[62:65], v[162:165], v[194:197], v[62:65]
	v_mfma_f32_16x16x32_bf16 v[58:61], v[170:173], v[194:197], v[58:61]
	v_mfma_f32_16x16x32_bf16 v[50:53], v[162:165], v[202:205], v[50:53]
	v_mfma_f32_16x16x32_bf16 v[42:45], v[170:173], v[202:205], v[42:45]
	v_mfma_f32_16x16x32_bf16 v[34:37], v[162:165], v[210:213], v[34:37]
	v_mfma_f32_16x16x32_bf16 v[26:29], v[170:173], v[210:213], v[26:29]
	v_mfma_f32_16x16x32_bf16 v[18:21], v[162:165], v[226:229], v[18:21]
	v_mfma_f32_16x16x32_bf16 v[10:13], v[170:173], v[226:229], v[10:13]
	v_mfma_f32_16x16x32_bf16 v[62:65], v[166:169], v[198:201], v[62:65]
	v_mfma_f32_16x16x32_bf16 v[58:61], v[174:177], v[198:201], v[58:61]
	v_mfma_f32_16x16x32_bf16 v[50:53], v[166:169], v[206:209], v[50:53]
	v_mfma_f32_16x16x32_bf16 v[42:45], v[174:177], v[206:209], v[42:45]
	v_mfma_f32_16x16x32_bf16 v[34:37], v[166:169], v[222:225], v[34:37]
	v_mfma_f32_16x16x32_bf16 v[26:29], v[174:177], v[222:225], v[26:29]
	v_mfma_f32_16x16x32_bf16 v[18:21], v[166:169], v[230:233], v[18:21]
	v_mfma_f32_16x16x32_bf16 v[10:13], v[174:177], v[230:233], v[10:13]
	s_setprio 0
	s_setprio 1
	v_mfma_f32_16x16x32_bf16 v[54:57], v[178:181], v[194:197], v[54:57]
	v_mfma_f32_16x16x32_bf16 v[46:49], v[186:189], v[194:197], v[46:49]
	v_mfma_f32_16x16x32_bf16 v[38:41], v[178:181], v[202:205], v[38:41]
	v_mfma_f32_16x16x32_bf16 v[30:33], v[186:189], v[202:205], v[30:33]
	v_mfma_f32_16x16x32_bf16 v[22:25], v[178:181], v[210:213], v[22:25]
	v_mfma_f32_16x16x32_bf16 v[14:17], v[186:189], v[210:213], v[14:17]
	v_mfma_f32_16x16x32_bf16 v[6:9], v[178:181], v[226:229], v[6:9]
	v_mfma_f32_16x16x32_bf16 v[2:5], v[186:189], v[226:229], v[2:5]
	v_mfma_f32_16x16x32_bf16 v[54:57], v[182:185], v[198:201], v[54:57]
	v_mfma_f32_16x16x32_bf16 v[46:49], v[190:193], v[198:201], v[46:49]
	v_mfma_f32_16x16x32_bf16 v[38:41], v[182:185], v[206:209], v[38:41]
	v_mfma_f32_16x16x32_bf16 v[30:33], v[190:193], v[206:209], v[30:33]
	v_mfma_f32_16x16x32_bf16 v[22:25], v[182:185], v[222:225], v[22:25]
	v_mfma_f32_16x16x32_bf16 v[14:17], v[190:193], v[222:225], v[14:17]
	v_mfma_f32_16x16x32_bf16 v[6:9], v[182:185], v[230:233], v[6:9]
	v_mfma_f32_16x16x32_bf16 v[2:5], v[190:193], v[230:233], v[2:5]
	s_setprio 0
	s_barrier
	s_add_i32 s55, 0, 0x18000
	v_add_u32_e32 v156, s55, v143
	s_add_i32 s56, 0, 0x1c000
	ds_read_b128 v[162:165], v156
	ds_read_b128 v[166:169], v156 offset:1024
	ds_read_b128 v[170:173], v156 offset:2048
	ds_read_b128 v[174:177], v156 offset:3072
	v_add_u32_e32 v156, s56, v143
	ds_read_b128 v[178:181], v156
	ds_read_b128 v[182:185], v156 offset:1024
	ds_read_b128 v[186:189], v156 offset:2048
	ds_read_b128 v[190:193], v156 offset:3072
	s_add_u32 s24, s24, 0x40000
	s_addc_u32 s25, s25, 0
	s_mov_b32 m0, s38
	v_lshl_add_u64 v[156:157], s[24:25], 0, v[134:135]
	ds_read_b128 v[194:197], v145 offset:32768
	ds_read_b128 v[198:201], v145 offset:33792
	ds_read_b128 v[202:205], v145 offset:34816
	ds_read_b128 v[206:209], v145 offset:35840
	ds_read_b128 v[210:213], v145 offset:36864
	ds_read_b128 v[222:225], v145 offset:37888
	ds_read_b128 v[226:229], v145 offset:38912
	ds_read_b128 v[230:233], v145 offset:39936
	global_load_lds_dwordx4 v[156:157], off
	v_lshl_add_u64 v[156:157], s[24:25], 0, v[132:133]
	s_mov_b32 m0, s39
	s_nop 0
	global_load_lds_dwordx4 v[156:157], off
	s_cmp_lg_u32 s98, 0
	s_cbranch_scc1 .Lrelax_g4_w3
	s_waitcnt vmcnt(8)
.Lback_g4_w3:
	s_waitcnt lgkmcnt(0)
	s_barrier
	s_setprio 1
	s_waitcnt lgkmcnt(0)
	v_mfma_f32_16x16x32_bf16 v[126:129], v[162:165], v[194:197], v[126:129]
	v_mfma_f32_16x16x32_bf16 v[122:125], v[170:173], v[194:197], v[122:125]
	v_mfma_f32_16x16x32_bf16 v[114:117], v[162:165], v[202:205], v[114:117]
	v_mfma_f32_16x16x32_bf16 v[106:109], v[170:173], v[202:205], v[106:109]
	v_mfma_f32_16x16x32_bf16 v[98:101], v[162:165], v[210:213], v[98:101]
	v_mfma_f32_16x16x32_bf16 v[90:93], v[170:173], v[210:213], v[90:93]
	v_mfma_f32_16x16x32_bf16 v[82:85], v[162:165], v[226:229], v[82:85]
	v_mfma_f32_16x16x32_bf16 v[74:77], v[170:173], v[226:229], v[74:77]
	v_mfma_f32_16x16x32_bf16 v[126:129], v[166:169], v[198:201], v[126:129]
	v_mfma_f32_16x16x32_bf16 v[122:125], v[174:177], v[198:201], v[122:125]
	v_mfma_f32_16x16x32_bf16 v[114:117], v[166:169], v[206:209], v[114:117]
	v_mfma_f32_16x16x32_bf16 v[106:109], v[174:177], v[206:209], v[106:109]
	v_mfma_f32_16x16x32_bf16 v[98:101], v[166:169], v[222:225], v[98:101]
	v_mfma_f32_16x16x32_bf16 v[90:93], v[174:177], v[222:225], v[90:93]
	v_mfma_f32_16x16x32_bf16 v[82:85], v[166:169], v[230:233], v[82:85]
	v_mfma_f32_16x16x32_bf16 v[74:77], v[174:177], v[230:233], v[74:77]
	s_setprio 0
	s_setprio 1
	v_mfma_f32_16x16x32_bf16 v[118:121], v[178:181], v[194:197], v[118:121]
	v_mfma_f32_16x16x32_bf16 v[110:113], v[186:189], v[194:197], v[110:113]
	v_mfma_f32_16x16x32_bf16 v[102:105], v[178:181], v[202:205], v[102:105]
	v_mfma_f32_16x16x32_bf16 v[94:97], v[186:189], v[202:205], v[94:97]
	v_mfma_f32_16x16x32_bf16 v[86:89], v[178:181], v[210:213], v[86:89]
	v_mfma_f32_16x16x32_bf16 v[78:81], v[186:189], v[210:213], v[78:81]
	v_mfma_f32_16x16x32_bf16 v[70:73], v[178:181], v[226:229], v[70:73]
	v_mfma_f32_16x16x32_bf16 v[66:69], v[186:189], v[226:229], v[66:69]
	v_mfma_f32_16x16x32_bf16 v[118:121], v[182:185], v[198:201], v[118:121]
	v_mfma_f32_16x16x32_bf16 v[110:113], v[190:193], v[198:201], v[110:113]
	v_mfma_f32_16x16x32_bf16 v[102:105], v[182:185], v[206:209], v[102:105]
	v_mfma_f32_16x16x32_bf16 v[94:97], v[190:193], v[206:209], v[94:97]
	v_mfma_f32_16x16x32_bf16 v[86:89], v[182:185], v[222:225], v[86:89]
	v_mfma_f32_16x16x32_bf16 v[78:81], v[190:193], v[222:225], v[78:81]
	v_mfma_f32_16x16x32_bf16 v[70:73], v[182:185], v[230:233], v[70:73]
	v_mfma_f32_16x16x32_bf16 v[66:69], v[190:193], v[230:233], v[66:69]
	s_setprio 0
	s_barrier
	s_add_i32 s24, s55, s30
	v_lshl_add_u64 v[140:141], v[140:141], 0, s[96:97]
	s_mov_b32 m0, s24
	ds_read_b128 v[194:197], v145 offset:49152
	ds_read_b128 v[198:201], v145 offset:50176
	ds_read_b128 v[202:205], v145 offset:51200
	ds_read_b128 v[206:209], v145 offset:52224
	ds_read_b128 v[210:213], v145 offset:53248
	ds_read_b128 v[222:225], v145 offset:54272
	ds_read_b128 v[226:229], v145 offset:55296
	ds_read_b128 v[230:233], v145 offset:56320
	global_load_lds_dwordx4 v[140:141], off
	s_add_i32 m0, s24, 0x2000
	s_add_u32 s22, s22, 0x40080
	v_lshl_add_u64 v[140:141], v[146:147], 0, s[96:97]
	s_addc_u32 s23, s23, 0
	s_add_i32 s24, s56, s30
	global_load_lds_dwordx4 v[140:141], off
	v_lshl_add_u64 v[140:141], s[22:23], 0, v[0:1]
	s_mov_b32 m0, s24
	s_nop 0
	global_load_lds_dwordx4 v[140:141], off
	v_lshl_add_u64 v[140:141], s[22:23], 0, v[130:131]
	s_add_i32 m0, s24, 0x2000
	s_nop 0
	global_load_lds_dwordx4 v[140:141], off
	v_lshl_add_u64 v[140:141], v[148:149], 0, s[96:97]
	s_mov_b32 m0, s40
	s_nop 0
	global_load_lds_dwordx4 v[140:141], off
	v_lshl_add_u64 v[140:141], v[154:155], 0, s[96:97]
	s_mov_b32 m0, s41
	s_nop 0
	global_load_lds_dwordx4 v[140:141], off
	s_waitcnt vmcnt(8)
	s_waitcnt lgkmcnt(0)
	s_barrier
	s_setprio 1
	s_waitcnt lgkmcnt(0)
	v_mfma_f32_16x16x32_bf16 v[62:65], v[162:165], v[194:197], v[62:65]
	v_mfma_f32_16x16x32_bf16 v[58:61], v[170:173], v[194:197], v[58:61]
	v_mfma_f32_16x16x32_bf16 v[50:53], v[162:165], v[202:205], v[50:53]
	v_mfma_f32_16x16x32_bf16 v[42:45], v[170:173], v[202:205], v[42:45]
	v_mfma_f32_16x16x32_bf16 v[34:37], v[162:165], v[210:213], v[34:37]
	v_mfma_f32_16x16x32_bf16 v[26:29], v[170:173], v[210:213], v[26:29]
	v_mfma_f32_16x16x32_bf16 v[18:21], v[162:165], v[226:229], v[18:21]
	v_mfma_f32_16x16x32_bf16 v[10:13], v[170:173], v[226:229], v[10:13]
	v_mfma_f32_16x16x32_bf16 v[62:65], v[166:169], v[198:201], v[62:65]
	v_mfma_f32_16x16x32_bf16 v[58:61], v[174:177], v[198:201], v[58:61]
	v_mfma_f32_16x16x32_bf16 v[50:53], v[166:169], v[206:209], v[50:53]
	v_mfma_f32_16x16x32_bf16 v[42:45], v[174:177], v[206:209], v[42:45]
	v_mfma_f32_16x16x32_bf16 v[34:37], v[166:169], v[222:225], v[34:37]
	v_mfma_f32_16x16x32_bf16 v[26:29], v[174:177], v[222:225], v[26:29]
	v_mfma_f32_16x16x32_bf16 v[18:21], v[166:169], v[230:233], v[18:21]
	v_mfma_f32_16x16x32_bf16 v[10:13], v[174:177], v[230:233], v[10:13]
	s_setprio 0
	s_setprio 1
	v_mfma_f32_16x16x32_bf16 v[54:57], v[178:181], v[194:197], v[54:57]
	v_mfma_f32_16x16x32_bf16 v[46:49], v[186:189], v[194:197], v[46:49]
	v_mfma_f32_16x16x32_bf16 v[38:41], v[178:181], v[202:205], v[38:41]
	v_mfma_f32_16x16x32_bf16 v[30:33], v[186:189], v[202:205], v[30:33]
	v_mfma_f32_16x16x32_bf16 v[22:25], v[178:181], v[210:213], v[22:25]
	v_mfma_f32_16x16x32_bf16 v[14:17], v[186:189], v[210:213], v[14:17]
	v_mfma_f32_16x16x32_bf16 v[6:9], v[178:181], v[226:229], v[6:9]
	v_mfma_f32_16x16x32_bf16 v[2:5], v[186:189], v[226:229], v[2:5]
	v_mfma_f32_16x16x32_bf16 v[54:57], v[182:185], v[198:201], v[54:57]
	v_mfma_f32_16x16x32_bf16 v[46:49], v[190:193], v[198:201], v[46:49]
	v_mfma_f32_16x16x32_bf16 v[38:41], v[182:185], v[206:209], v[38:41]
	v_mfma_f32_16x16x32_bf16 v[30:33], v[190:193], v[206:209], v[30:33]
	v_mfma_f32_16x16x32_bf16 v[22:25], v[182:185], v[222:225], v[22:25]
	v_mfma_f32_16x16x32_bf16 v[14:17], v[190:193], v[222:225], v[14:17]
	v_mfma_f32_16x16x32_bf16 v[6:9], v[182:185], v[230:233], v[6:9]
	v_mfma_f32_16x16x32_bf16 v[2:5], v[190:193], v[230:233], v[2:5]
	s_setprio 0
	s_barrier
	s_add_i32 s49, s49, 2
	s_add_u32 s47, s47, 0x100
	s_addc_u32 s48, s48, 0
	s_add_u32 s20, s20, 0x100
	s_addc_u32 s21, s21, 0
	s_cmp_gt_u32 s49, 13
	s_cbranch_scc0 .LBB0_353
	s_add_u32 s20, s45, 0x40080
	s_addc_u32 s21, s13, 0
	s_and_b64 vcc, exec, s[8:9]
	s_cbranch_vccz .LBB0_356
	s_barrier
.LBB0_356:
	v_lshl_add_u64 v[140:141], s[20:21], 0, v[138:139]
	s_add_i32 m0, s19, 0xc000
	s_nop 0
	global_load_lds_dwordx4 v[140:141], off
	v_lshl_add_u64 v[140:141], s[20:21], 0, v[136:137]
	s_add_i32 m0, s19, 0xe000
	s_nop 0
	global_load_lds_dwordx4 v[140:141], off
	v_lshl_or_b32 v140, s44, 8, v144
	v_ashrrev_i32_e32 v141, 31, v140
	v_lshl_add_u32 v154, s18, 8, v142
	v_lshl_add_u64 v[140:141], v[140:141], 1, s[6:7]
	s_movk_i32 s11, 0x1800
	v_mad_i64_i32 v[146:147], s[20:21], v154, s11, v[140:141]
	v_pk_add_f32 v[128:129], v[128:129], 0 op_sel_hi:[1,0]
	v_pk_add_f32 v[126:127], v[126:127], 0 op_sel_hi:[1,0]
	v_pk_add_f32 v[148:149], v[124:125], 0 op_sel_hi:[1,0]
	v_pk_add_f32 v[124:125], v[122:123], 0 op_sel_hi:[1,0]
	v_cvt_pk_bf16_f32 v122, v126, v127
	v_cvt_pk_bf16_f32 v123, v128, v129
	v_pk_add_f32 v[118:119], v[118:119], 0 op_sel_hi:[1,0]
	v_cvt_pk_bf16_f32 v124, v124, v125
	v_cvt_pk_bf16_f32 v125, v148, v149
	global_store_dwordx4 v[146:147], v[122:125], off nt
	v_pk_add_f32 v[120:121], v[120:121], 0 op_sel_hi:[1,0]
	v_pk_add_f32 v[114:115], v[114:115], 0 op_sel_hi:[1,0]
	v_pk_add_f32 v[122:123], v[112:113], 0 op_sel_hi:[1,0]
	v_pk_add_f32 v[112:113], v[110:111], 0 op_sel_hi:[1,0]
	v_cvt_pk_bf16_f32 v110, v118, v119
	v_cvt_pk_bf16_f32 v111, v120, v121
	v_pk_add_f32 v[102:103], v[102:103], 0 op_sel_hi:[1,0]
	v_cvt_pk_bf16_f32 v112, v112, v113
	v_cvt_pk_bf16_f32 v113, v122, v123
	global_store_dwordx4 v[146:147], v[110:113], off offset:256 nt
	v_pk_add_f32 v[104:105], v[104:105], 0 op_sel_hi:[1,0]
	v_pk_add_f32 v[98:99], v[98:99], 0 op_sel_hi:[1,0]
	v_or_b32_e32 v110, 16, v154
	v_mad_i64_i32 v[110:111], s[20:21], v110, s11, v[140:141]
	v_pk_add_f32 v[112:113], v[116:117], 0 op_sel_hi:[1,0]
	v_pk_add_f32 v[116:117], v[108:109], 0 op_sel_hi:[1,0]
	v_pk_add_f32 v[108:109], v[106:107], 0 op_sel_hi:[1,0]
	v_cvt_pk_bf16_f32 v106, v114, v115
	v_cvt_pk_bf16_f32 v107, v112, v113
	v_pk_add_f32 v[86:87], v[86:87], 0 op_sel_hi:[1,0]
	v_cvt_pk_bf16_f32 v108, v108, v109
	v_cvt_pk_bf16_f32 v109, v116, v117
	global_store_dwordx4 v[110:111], v[106:109], off nt
	v_pk_add_f32 v[88:89], v[88:89], 0 op_sel_hi:[1,0]
	v_pk_add_f32 v[82:83], v[82:83], 0 op_sel_hi:[1,0]
	v_pk_add_f32 v[106:107], v[96:97], 0 op_sel_hi:[1,0]
	v_pk_add_f32 v[96:97], v[94:95], 0 op_sel_hi:[1,0]
	v_cvt_pk_bf16_f32 v94, v102, v103
	v_cvt_pk_bf16_f32 v95, v104, v105
	v_pk_add_f32 v[70:71], v[70:71], 0 op_sel_hi:[1,0]
	v_cvt_pk_bf16_f32 v96, v96, v97
	v_cvt_pk_bf16_f32 v97, v106, v107
	global_store_dwordx4 v[110:111], v[94:97], off offset:256 nt
	v_pk_add_f32 v[72:73], v[72:73], 0 op_sel_hi:[1,0]
	v_pk_add_f32 v[64:65], v[64:65], 0 op_sel_hi:[1,0]
	v_or_b32_e32 v94, 32, v154
	v_mad_i64_i32 v[94:95], s[20:21], v94, s11, v[140:141]
	v_pk_add_f32 v[96:97], v[100:101], 0 op_sel_hi:[1,0]
	v_pk_add_f32 v[100:101], v[92:93], 0 op_sel_hi:[1,0]
	v_pk_add_f32 v[92:93], v[90:91], 0 op_sel_hi:[1,0]
	v_cvt_pk_bf16_f32 v90, v98, v99
	v_cvt_pk_bf16_f32 v91, v96, v97
	v_pk_add_f32 v[62:63], v[62:63], 0 op_sel_hi:[1,0]
	v_cvt_pk_bf16_f32 v92, v92, v93
	v_cvt_pk_bf16_f32 v93, v100, v101
	global_store_dwordx4 v[94:95], v[90:93], off nt
	v_pk_add_f32 v[54:55], v[54:55], 0 op_sel_hi:[1,0]
	v_pk_add_f32 v[56:57], v[56:57], 0 op_sel_hi:[1,0]
	v_pk_add_f32 v[90:91], v[80:81], 0 op_sel_hi:[1,0]
	v_pk_add_f32 v[80:81], v[78:79], 0 op_sel_hi:[1,0]
	v_cvt_pk_bf16_f32 v78, v86, v87
	v_cvt_pk_bf16_f32 v79, v88, v89
	v_pk_add_f32 v[50:51], v[50:51], 0 op_sel_hi:[1,0]
	v_cvt_pk_bf16_f32 v80, v80, v81
	v_cvt_pk_bf16_f32 v81, v90, v91
	global_store_dwordx4 v[94:95], v[78:81], off offset:256 nt
	v_pk_add_f32 v[38:39], v[38:39], 0 op_sel_hi:[1,0]
	v_pk_add_f32 v[40:41], v[40:41], 0 op_sel_hi:[1,0]
	v_or_b32_e32 v78, 48, v154
	v_mad_i64_i32 v[78:79], s[20:21], v78, s11, v[140:141]
	v_pk_add_f32 v[80:81], v[84:85], 0 op_sel_hi:[1,0]
	v_pk_add_f32 v[84:85], v[76:77], 0 op_sel_hi:[1,0]
	v_pk_add_f32 v[76:77], v[74:75], 0 op_sel_hi:[1,0]
	v_cvt_pk_bf16_f32 v74, v82, v83
	v_cvt_pk_bf16_f32 v75, v80, v81
	v_pk_add_f32 v[34:35], v[34:35], 0 op_sel_hi:[1,0]
	v_cvt_pk_bf16_f32 v76, v76, v77
	v_cvt_pk_bf16_f32 v77, v84, v85
	global_store_dwordx4 v[78:79], v[74:77], off nt
	v_pk_add_f32 v[22:23], v[22:23], 0 op_sel_hi:[1,0]
	v_pk_add_f32 v[24:25], v[24:25], 0 op_sel_hi:[1,0]
	v_pk_add_f32 v[74:75], v[68:69], 0 op_sel_hi:[1,0]
	v_pk_add_f32 v[68:69], v[66:67], 0 op_sel_hi:[1,0]
	v_cvt_pk_bf16_f32 v66, v70, v71
	v_cvt_pk_bf16_f32 v67, v72, v73
	v_pk_add_f32 v[18:19], v[18:19], 0 op_sel_hi:[1,0]
	v_cvt_pk_bf16_f32 v68, v68, v69
	v_cvt_pk_bf16_f32 v69, v74, v75
	global_store_dwordx4 v[78:79], v[66:69], off offset:256 nt
	s_andn2_b64 vcc, exec, s[0:1]
	s_mov_b64 s[0:1], -1
	v_add_u32_e32 v66, 0x80, v154
	v_mad_i64_i32 v[66:67], s[20:21], v66, s11, v[140:141]
	v_pk_add_f32 v[68:69], v[60:61], 0 op_sel_hi:[1,0]
	v_pk_add_f32 v[60:61], v[58:59], 0 op_sel_hi:[1,0]
	v_cvt_pk_bf16_f32 v58, v62, v63
	v_cvt_pk_bf16_f32 v59, v64, v65
	s_movk_i32 s46, 0xd000
	v_cvt_pk_bf16_f32 v60, v60, v61
	v_cvt_pk_bf16_f32 v61, v68, v69
	global_store_dwordx4 v[66:67], v[58:61], off nt
	s_movk_i32 s47, 0xec00
	s_movk_i32 s55, 0xf000
	v_pk_add_f32 v[58:59], v[48:49], 0 op_sel_hi:[1,0]
	v_pk_add_f32 v[48:49], v[46:47], 0 op_sel_hi:[1,0]
	v_cvt_pk_bf16_f32 v46, v54, v55
	v_cvt_pk_bf16_f32 v47, v56, v57
	v_pk_add_f32 v[8:9], v[8:9], 0 op_sel_hi:[1,0]
	v_cvt_pk_bf16_f32 v48, v48, v49
	v_cvt_pk_bf16_f32 v49, v58, v59
	global_store_dwordx4 v[66:67], v[46:49], off offset:256 nt
	v_pk_add_f32 v[6:7], v[6:7], 0 op_sel_hi:[1,0]
	s_nop 0
	v_add_u32_e32 v46, 0x90, v154
	v_mad_i64_i32 v[46:47], s[20:21], v46, s11, v[140:141]
	v_pk_add_f32 v[48:49], v[52:53], 0 op_sel_hi:[1,0]
	v_pk_add_f32 v[52:53], v[44:45], 0 op_sel_hi:[1,0]
	v_pk_add_f32 v[44:45], v[42:43], 0 op_sel_hi:[1,0]
	v_cvt_pk_bf16_f32 v42, v50, v51
	v_cvt_pk_bf16_f32 v43, v48, v49
	s_nop 0
	v_cvt_pk_bf16_f32 v44, v44, v45
	v_cvt_pk_bf16_f32 v45, v52, v53
	global_store_dwordx4 v[46:47], v[42:45], off nt
	s_nop 1
	v_pk_add_f32 v[42:43], v[32:33], 0 op_sel_hi:[1,0]
	v_pk_add_f32 v[32:33], v[30:31], 0 op_sel_hi:[1,0]
	v_cvt_pk_bf16_f32 v30, v38, v39
	v_cvt_pk_bf16_f32 v31, v40, v41
	s_nop 0
	v_cvt_pk_bf16_f32 v32, v32, v33
	v_cvt_pk_bf16_f32 v33, v42, v43
	global_store_dwordx4 v[46:47], v[30:33], off offset:256 nt
	s_nop 1
	v_add_u32_e32 v30, 0xa0, v154
	v_mad_i64_i32 v[30:31], s[20:21], v30, s11, v[140:141]
	v_pk_add_f32 v[32:33], v[36:37], 0 op_sel_hi:[1,0]
	v_pk_add_f32 v[36:37], v[28:29], 0 op_sel_hi:[1,0]
	v_pk_add_f32 v[28:29], v[26:27], 0 op_sel_hi:[1,0]
	v_cvt_pk_bf16_f32 v26, v34, v35
	v_cvt_pk_bf16_f32 v27, v32, v33
	s_nop 0
	v_cvt_pk_bf16_f32 v28, v28, v29
	v_cvt_pk_bf16_f32 v29, v36, v37
	global_store_dwordx4 v[30:31], v[26:29], off nt
	s_nop 1
	v_pk_add_f32 v[26:27], v[16:17], 0 op_sel_hi:[1,0]
	v_pk_add_f32 v[16:17], v[14:15], 0 op_sel_hi:[1,0]
	v_cvt_pk_bf16_f32 v14, v22, v23
	v_cvt_pk_bf16_f32 v15, v24, v25
	s_nop 0
	v_cvt_pk_bf16_f32 v16, v16, v17
	v_cvt_pk_bf16_f32 v17, v26, v27
	global_store_dwordx4 v[30:31], v[14:17], off offset:256 nt
	s_nop 1
	v_add_u32_e32 v14, 0xb0, v154
	v_mad_i64_i32 v[14:15], s[20:21], v14, s11, v[140:141]
	v_pk_add_f32 v[16:17], v[20:21], 0 op_sel_hi:[1,0]
	v_pk_add_f32 v[20:21], v[12:13], 0 op_sel_hi:[1,0]
	v_pk_add_f32 v[12:13], v[10:11], 0 op_sel_hi:[1,0]
	v_cvt_pk_bf16_f32 v10, v18, v19
	v_cvt_pk_bf16_f32 v11, v16, v17
	s_nop 0
	v_cvt_pk_bf16_f32 v12, v12, v13
	v_cvt_pk_bf16_f32 v13, v20, v21
	global_store_dwordx4 v[14:15], v[10:13], off nt
	s_nop 1
	v_pk_add_f32 v[10:11], v[4:5], 0 op_sel_hi:[1,0]
	v_pk_add_f32 v[4:5], v[2:3], 0 op_sel_hi:[1,0]
	v_cvt_pk_bf16_f32 v2, v6, v7
	v_cvt_pk_bf16_f32 v3, v8, v9
	s_nop 0
	v_cvt_pk_bf16_f32 v4, v4, v5
	v_cvt_pk_bf16_f32 v5, v10, v11
	global_store_dwordx4 v[14:15], v[2:5], off offset:256 nt
	s_mov_b32 s98, 1
	s_cbranch_vccnz .LBB0_349
	s_andn2_b64 vcc, exec, s[4:5]
	s_cbranch_vccnz .LBB0_348
	s_barrier
	s_branch .LBB0_348
.Lrelax_g4_w1:
	s_waitcnt vmcnt(24)
	s_branch .Lback_g4_w1
.Lrelax_g4_w2:
	s_waitcnt vmcnt(24)
	s_branch .Lback_g4_w2

.LBB0_381:
	s_add_u32 s22, s20, 0xfff00080
	s_addc_u32 s23, s21, -1
	s_add_i32 s57, 0, 0x10000
	s_cmp_eq_u32 s56, 60
	s_cselect_b32 s25, s13, s23
	s_cselect_b32 s24, s47, s22
	s_cselect_b32 s23, s11, s55
	s_cselect_b32 s22, s48, s49
	s_add_i32 s60, 0, 0x14000
	v_add_u32_e32 v134, s57, v176
	v_add_u32_e32 v179, s60, v176
	ds_read_b128 v[122:125], v134
	ds_read_b128 v[126:129], v134 offset:1024
	ds_read_b128 v[130:133], v134 offset:2048
	ds_read_b128 v[134:137], v134 offset:3072
	ds_read_b128 v[146:149], v179
	ds_read_b128 v[154:157], v179 offset:1024
	ds_read_b128 v[172:175], v179 offset:2048
	ds_read_b128 v[180:183], v179 offset:3072
	v_lshl_add_u64 v[212:213], s[20:21], 0, v[170:171]
	s_add_i32 m0, s19, 0xc000
	ds_read_b128 v[184:187], v178
	ds_read_b128 v[188:191], v178 offset:1024
	ds_read_b128 v[192:195], v178 offset:2048
	ds_read_b128 v[196:199], v178 offset:3072
	ds_read_b128 v[200:203], v178 offset:4096
	ds_read_b128 v[204:207], v178 offset:5120
	ds_read_b128 v[208:211], v178 offset:6144
	ds_read_b128 v[222:225], v178 offset:7168
	s_cmp_lg_u32 s98, 0
	s_cbranch_scc1 .Lgc_skip_g5
	global_load_lds_dwordx4 v[212:213], off
	v_lshl_add_u64 v[212:213], s[20:21], 0, v[168:169]
	s_add_i32 m0, s19, 0xe000
	s_nop 0
	global_load_lds_dwordx4 v[212:213], off

.Lback_g5_w2:
	s_waitcnt lgkmcnt(0)
	s_barrier
	s_setprio 1
	s_waitcnt lgkmcnt(0)
	v_mfma_f32_16x16x32_bf16 v[62:65], v[122:125], v[184:187], v[62:65]
	v_mfma_f32_16x16x32_bf16 v[58:61], v[130:133], v[184:187], v[58:61]
	v_mfma_f32_16x16x32_bf16 v[54:57], v[122:125], v[192:195], v[54:57]
	v_mfma_f32_16x16x32_bf16 v[42:45], v[130:133], v[192:195], v[42:45]
	v_mfma_f32_16x16x32_bf16 v[34:37], v[122:125], v[200:203], v[34:37]
	v_mfma_f32_16x16x32_bf16 v[26:29], v[130:133], v[200:203], v[26:29]
	v_mfma_f32_16x16x32_bf16 v[22:25], v[122:125], v[208:211], v[22:25]
	v_mfma_f32_16x16x32_bf16 v[10:13], v[130:133], v[208:211], v[10:13]
	v_mfma_f32_16x16x32_bf16 v[62:65], v[126:129], v[188:191], v[62:65]
	v_mfma_f32_16x16x32_bf16 v[58:61], v[134:137], v[188:191], v[58:61]
	v_mfma_f32_16x16x32_bf16 v[54:57], v[126:129], v[196:199], v[54:57]
	v_mfma_f32_16x16x32_bf16 v[42:45], v[134:137], v[196:199], v[42:45]
	v_mfma_f32_16x16x32_bf16 v[34:37], v[126:129], v[204:207], v[34:37]
	v_mfma_f32_16x16x32_bf16 v[26:29], v[134:137], v[204:207], v[26:29]
	v_mfma_f32_16x16x32_bf16 v[22:25], v[126:129], v[222:225], v[22:25]
	v_mfma_f32_16x16x32_bf16 v[10:13], v[134:137], v[222:225], v[10:13]
	s_setprio 0
	s_setprio 1
	v_mfma_f32_16x16x32_bf16 v[50:53], v[146:149], v[184:187], v[50:53]
	v_mfma_f32_16x16x32_bf16 v[46:49], v[172:175], v[184:187], v[46:49]
	v_mfma_f32_16x16x32_bf16 v[38:41], v[146:149], v[192:195], v[38:41]
	v_mfma_f32_16x16x32_bf16 v[30:33], v[172:175], v[192:195], v[30:33]
	v_mfma_f32_16x16x32_bf16 v[18:21], v[146:149], v[200:203], v[18:21]
	v_mfma_f32_16x16x32_bf16 v[14:17], v[172:175], v[200:203], v[14:17]
	v_mfma_f32_16x16x32_bf16 v[6:9], v[146:149], v[208:211], v[6:9]
	v_mfma_f32_16x16x32_bf16 v[2:5], v[172:175], v[208:211], v[2:5]
	v_mfma_f32_16x16x32_bf16 v[50:53], v[154:157], v[188:191], v[50:53]
	v_mfma_f32_16x16x32_bf16 v[46:49], v[180:183], v[188:191], v[46:49]
	v_mfma_f32_16x16x32_bf16 v[38:41], v[154:157], v[196:199], v[38:41]
	v_mfma_f32_16x16x32_bf16 v[30:33], v[180:183], v[196:199], v[30:33]
	v_mfma_f32_16x16x32_bf16 v[18:21], v[154:157], v[204:207], v[18:21]
	v_mfma_f32_16x16x32_bf16 v[14:17], v[180:183], v[204:207], v[14:17]
	v_mfma_f32_16x16x32_bf16 v[6:9], v[154:157], v[222:225], v[6:9]
	v_mfma_f32_16x16x32_bf16 v[2:5], v[180:183], v[222:225], v[2:5]
	s_setprio 0
	s_barrier
	s_add_i32 s57, 0, 0x18000
	s_add_i32 s58, 0, 0x1c000
	v_add_u32_e32 v134, s57, v176
	v_add_u32_e32 v179, s58, v176
	ds_read_b128 v[122:125], v134
	ds_read_b128 v[126:129], v134 offset:1024
	ds_read_b128 v[130:133], v134 offset:2048
	ds_read_b128 v[134:137], v134 offset:3072
	ds_read_b128 v[146:149], v179
	ds_read_b128 v[154:157], v179 offset:1024
	ds_read_b128 v[172:175], v179 offset:2048
	ds_read_b128 v[180:183], v179 offset:3072
	s_add_u32 s24, s24, 0x100000
	s_addc_u32 s25, s25, 0
	s_mov_b32 m0, s38
	v_lshl_add_u64 v[232:233], s[24:25], 0, v[162:163]
	ds_read_b128 v[184:187], v178 offset:32768
	ds_read_b128 v[188:191], v178 offset:33792
	ds_read_b128 v[192:195], v178 offset:34816
	ds_read_b128 v[196:199], v178 offset:35840
	ds_read_b128 v[200:203], v178 offset:36864
	ds_read_b128 v[204:207], v178 offset:37888
	ds_read_b128 v[208:211], v178 offset:38912
	ds_read_b128 v[222:225], v178 offset:39936
	global_load_lds_dwordx4 v[232:233], off
	v_lshl_add_u64 v[232:233], s[24:25], 0, v[164:165]
	s_mov_b32 m0, s39
	s_nop 0
	global_load_lds_dwordx4 v[232:233], off
	s_cmp_lg_u32 s98, 0
	s_cbranch_scc1 .Lrelax_g5_w3
	s_waitcnt vmcnt(8)
.Lback_g5_w3:
	s_waitcnt lgkmcnt(0)
	s_barrier
	s_setprio 1
	s_waitcnt lgkmcnt(0)
	v_mfma_f32_16x16x32_bf16 v[142:145], v[122:125], v[184:187], v[142:145]
	v_mfma_f32_16x16x32_bf16 v[138:141], v[130:133], v[184:187], v[138:141]
	v_mfma_f32_16x16x32_bf16 v[118:121], v[122:125], v[192:195], v[118:121]
	v_mfma_f32_16x16x32_bf16 v[106:109], v[130:133], v[192:195], v[106:109]
	v_mfma_f32_16x16x32_bf16 v[98:101], v[122:125], v[200:203], v[98:101]
	v_mfma_f32_16x16x32_bf16 v[90:93], v[130:133], v[200:203], v[90:93]
	v_mfma_f32_16x16x32_bf16 v[86:89], v[122:125], v[208:211], v[86:89]
	v_mfma_f32_16x16x32_bf16 v[74:77], v[130:133], v[208:211], v[74:77]
	v_mfma_f32_16x16x32_bf16 v[142:145], v[126:129], v[188:191], v[142:145]
	v_mfma_f32_16x16x32_bf16 v[138:141], v[134:137], v[188:191], v[138:141]
	v_mfma_f32_16x16x32_bf16 v[118:121], v[126:129], v[196:199], v[118:121]
	v_mfma_f32_16x16x32_bf16 v[106:109], v[134:137], v[196:199], v[106:109]
	v_mfma_f32_16x16x32_bf16 v[98:101], v[126:129], v[204:207], v[98:101]
	v_mfma_f32_16x16x32_bf16 v[90:93], v[134:137], v[204:207], v[90:93]
	v_mfma_f32_16x16x32_bf16 v[86:89], v[126:129], v[222:225], v[86:89]
	v_mfma_f32_16x16x32_bf16 v[74:77], v[134:137], v[222:225], v[74:77]
	s_setprio 0
	s_setprio 1
	v_mfma_f32_16x16x32_bf16 v[114:117], v[146:149], v[184:187], v[114:117]
	v_mfma_f32_16x16x32_bf16 v[110:113], v[172:175], v[184:187], v[110:113]
	v_mfma_f32_16x16x32_bf16 v[102:105], v[146:149], v[192:195], v[102:105]
	v_mfma_f32_16x16x32_bf16 v[94:97], v[172:175], v[192:195], v[94:97]
	v_mfma_f32_16x16x32_bf16 v[82:85], v[146:149], v[200:203], v[82:85]
	v_mfma_f32_16x16x32_bf16 v[78:81], v[172:175], v[200:203], v[78:81]
	v_mfma_f32_16x16x32_bf16 v[70:73], v[146:149], v[208:211], v[70:73]
	v_mfma_f32_16x16x32_bf16 v[66:69], v[172:175], v[208:211], v[66:69]
	v_mfma_f32_16x16x32_bf16 v[114:117], v[154:157], v[188:191], v[114:117]
	v_mfma_f32_16x16x32_bf16 v[110:113], v[180:183], v[188:191], v[110:113]
	v_mfma_f32_16x16x32_bf16 v[102:105], v[154:157], v[196:199], v[102:105]
	v_mfma_f32_16x16x32_bf16 v[94:97], v[180:183], v[196:199], v[94:97]
	v_mfma_f32_16x16x32_bf16 v[82:85], v[154:157], v[204:207], v[82:85]
	v_mfma_f32_16x16x32_bf16 v[78:81], v[180:183], v[204:207], v[78:81]
	v_mfma_f32_16x16x32_bf16 v[70:73], v[154:157], v[222:225], v[70:73]
	v_mfma_f32_16x16x32_bf16 v[66:69], v[180:183], v[222:225], v[66:69]
	s_setprio 0
	s_barrier
	s_add_i32 s24, s57, s31
	v_lshl_add_u64 v[212:213], v[212:213], 0, s[96:97]
	s_mov_b32 m0, s24
	ds_read_b128 v[184:187], v178 offset:49152
	ds_read_b128 v[188:191], v178 offset:50176
	ds_read_b128 v[192:195], v178 offset:51200
	ds_read_b128 v[196:199], v178 offset:52224
	ds_read_b128 v[200:203], v178 offset:53248
	ds_read_b128 v[204:207], v178 offset:54272
	ds_read_b128 v[208:211], v178 offset:55296
	ds_read_b128 v[222:225], v178 offset:56320
	global_load_lds_dwordx4 v[212:213], off
	s_add_i32 m0, s24, 0x2000
	s_add_u32 s22, s22, 0x100080
	v_lshl_add_u64 v[212:213], v[226:227], 0, s[96:97]
	s_addc_u32 s23, s23, 0
	s_add_i32 s24, s58, s31
	global_load_lds_dwordx4 v[212:213], off
	v_lshl_add_u64 v[212:213], s[22:23], 0, v[0:1]
	s_mov_b32 m0, s24
	s_nop 0
	global_load_lds_dwordx4 v[212:213], off
	v_lshl_add_u64 v[212:213], s[22:23], 0, v[166:167]
	s_add_i32 m0, s24, 0x2000
	s_nop 0
	global_load_lds_dwordx4 v[212:213], off
	v_lshl_add_u64 v[212:213], v[228:229], 0, s[96:97]
	s_mov_b32 m0, s42
	s_nop 0
	global_load_lds_dwordx4 v[212:213], off
	v_lshl_add_u64 v[212:213], v[230:231], 0, s[96:97]
	s_mov_b32 m0, s43
	s_nop 0
	global_load_lds_dwordx4 v[212:213], off
	s_waitcnt vmcnt(8)
	s_waitcnt lgkmcnt(0)
	s_barrier
	s_setprio 1
	s_waitcnt lgkmcnt(0)
	v_mfma_f32_16x16x32_bf16 v[62:65], v[122:125], v[184:187], v[62:65]
	v_mfma_f32_16x16x32_bf16 v[58:61], v[130:133], v[184:187], v[58:61]
	v_mfma_f32_16x16x32_bf16 v[54:57], v[122:125], v[192:195], v[54:57]
	v_mfma_f32_16x16x32_bf16 v[42:45], v[130:133], v[192:195], v[42:45]
	v_mfma_f32_16x16x32_bf16 v[34:37], v[122:125], v[200:203], v[34:37]
	v_mfma_f32_16x16x32_bf16 v[26:29], v[130:133], v[200:203], v[26:29]
	v_mfma_f32_16x16x32_bf16 v[22:25], v[122:125], v[208:211], v[22:25]
	v_mfma_f32_16x16x32_bf16 v[10:13], v[130:133], v[208:211], v[10:13]
	v_mfma_f32_16x16x32_bf16 v[62:65], v[126:129], v[188:191], v[62:65]
	v_mfma_f32_16x16x32_bf16 v[58:61], v[134:137], v[188:191], v[58:61]
	v_mfma_f32_16x16x32_bf16 v[54:57], v[126:129], v[196:199], v[54:57]
	v_mfma_f32_16x16x32_bf16 v[42:45], v[134:137], v[196:199], v[42:45]
	v_mfma_f32_16x16x32_bf16 v[34:37], v[126:129], v[204:207], v[34:37]
	v_mfma_f32_16x16x32_bf16 v[26:29], v[134:137], v[204:207], v[26:29]
	v_mfma_f32_16x16x32_bf16 v[22:25], v[126:129], v[222:225], v[22:25]
	v_mfma_f32_16x16x32_bf16 v[10:13], v[134:137], v[222:225], v[10:13]
	s_setprio 0
	s_setprio 1
	v_mfma_f32_16x16x32_bf16 v[50:53], v[146:149], v[184:187], v[50:53]
	v_mfma_f32_16x16x32_bf16 v[46:49], v[172:175], v[184:187], v[46:49]
	v_mfma_f32_16x16x32_bf16 v[38:41], v[146:149], v[192:195], v[38:41]
	v_mfma_f32_16x16x32_bf16 v[30:33], v[172:175], v[192:195], v[30:33]
	v_mfma_f32_16x16x32_bf16 v[18:21], v[146:149], v[200:203], v[18:21]
	v_mfma_f32_16x16x32_bf16 v[14:17], v[172:175], v[200:203], v[14:17]
	v_mfma_f32_16x16x32_bf16 v[6:9], v[146:149], v[208:211], v[6:9]
	v_mfma_f32_16x16x32_bf16 v[2:5], v[172:175], v[208:211], v[2:5]
	v_mfma_f32_16x16x32_bf16 v[50:53], v[154:157], v[188:191], v[50:53]
	v_mfma_f32_16x16x32_bf16 v[46:49], v[180:183], v[188:191], v[46:49]
	v_mfma_f32_16x16x32_bf16 v[38:41], v[154:157], v[196:199], v[38:41]
	v_mfma_f32_16x16x32_bf16 v[30:33], v[180:183], v[196:199], v[30:33]
	v_mfma_f32_16x16x32_bf16 v[18:21], v[154:157], v[204:207], v[18:21]
	v_mfma_f32_16x16x32_bf16 v[14:17], v[180:183], v[204:207], v[14:17]
	v_mfma_f32_16x16x32_bf16 v[6:9], v[154:157], v[222:225], v[6:9]
	v_mfma_f32_16x16x32_bf16 v[2:5], v[180:183], v[222:225], v[2:5]
	s_setprio 0
	s_barrier
	s_add_i32 s56, s56, 2
	s_add_u32 s49, s49, 0x100
	s_addc_u32 s55, s55, 0
	s_add_u32 s20, s20, 0x100
	s_addc_u32 s21, s21, 0
	s_cmp_gt_u32 s56, 61
	s_cbranch_scc0 .LBB0_381
	s_add_u32 s20, s47, 0x100080
	s_addc_u32 s21, s13, 0
	s_and_b64 vcc, exec, s[8:9]
	s_movk_i32 s47, 0xec00
	s_movk_i32 s55, 0xf000
	s_cbranch_vccz .LBB0_384
	s_barrier
.LBB0_384:
	v_lshl_add_u64 v[212:213], s[20:21], 0, v[170:171]
	s_add_i32 m0, s19, 0xc000
	s_nop 0
	global_load_lds_dwordx4 v[212:213], off
	v_lshl_add_u64 v[212:213], s[20:21], 0, v[168:169]
	s_add_i32 m0, s19, 0xe000
	s_nop 0
	global_load_lds_dwordx4 v[212:213], off
	v_lshl_add_u32 v172, s18, 8, v159
	v_lshl_or_b32 v122, s46, 8, v177
	v_ashrrev_i32_e32 v173, 31, v172
	v_ashrrev_i32_e32 v123, 31, v122
	v_lshlrev_b64 v[124:125], 11, v[172:173]
	v_lshl_add_u64 v[124:125], s[6:7], 0, v[124:125]
	v_lshlrev_b64 v[174:175], 1, v[122:123]
	s_ashr_i32 s11, s18, 4
	v_lshl_add_u64 v[154:155], v[124:125], 0, v[174:175]
	s_mul_hi_i32 s13, s11, 0x6000
	s_mulk_i32 s11, 0x6000
	s_add_u32 s20, s40, s11
	s_addc_u32 s21, s41, s13
	v_lshl_add_u64 v[122:123], v[122:123], 2, s[20:21]
	global_load_dwordx4 v[134:137], v[122:123], off
	global_load_dwordx4 v[130:133], v[122:123], off offset:16
	global_load_dwordx4 v[126:129], v[122:123], off offset:512
	s_nop 0
	global_load_dwordx4 v[122:125], v[122:123], off offset:528
	v_mov_b64_e32 v[172:173], v[154:155]
	v_mov_b64_e32 v[174:175], v[172:173]
	global_load_dwordx4 v[146:149], v[174:175], off
	global_load_dwordx4 v[154:157], v[174:175], off offset:256
	s_mov_b32 s20, 0x8000
	s_mov_b32 s21, 0
	v_lshl_add_u64 v[174:175], v[172:173], 0, s[20:21]
	global_load_dwordx4 v[180:183], v[174:175], off
	global_load_dwordx4 v[184:187], v[174:175], off offset:256
	s_mov_b32 s20, 0x10000
	s_mov_b32 s21, 0
	v_lshl_add_u64 v[174:175], v[172:173], 0, s[20:21]
	global_load_dwordx4 v[188:191], v[174:175], off
	global_load_dwordx4 v[192:195], v[174:175], off offset:256
	s_mov_b32 s20, 0x18000
	s_mov_b32 s21, 0
	v_lshl_add_u64 v[174:175], v[172:173], 0, s[20:21]
	global_load_dwordx4 v[196:199], v[174:175], off
	global_load_dwordx4 v[200:203], v[174:175], off offset:256
	s_mov_b32 s20, 0x40000
	s_mov_b32 s21, 0
	v_lshl_add_u64 v[174:175], v[172:173], 0, s[20:21]
	global_load_dwordx4 v[204:207], v[174:175], off
	global_load_dwordx4 v[208:211], v[174:175], off offset:256
	s_mov_b32 s20, 0x48000
	s_mov_b32 s21, 0
	v_lshl_add_u64 v[174:175], v[172:173], 0, s[20:21]
	global_load_dwordx4 v[222:225], v[174:175], off
	global_load_dwordx4 v[226:229], v[174:175], off offset:256
	s_mov_b32 s20, 0x50000
	s_mov_b32 s21, 0
	v_lshl_add_u64 v[174:175], v[172:173], 0, s[20:21]
	global_load_dwordx4 v[230:233], v[174:175], off
	global_load_dwordx4 v[234:237], v[174:175], off offset:256
	s_mov_b32 s20, 0x58000
	s_mov_b32 s21, 0
	v_lshl_add_u64 v[174:175], v[172:173], 0, s[20:21]
	global_load_dwordx4 v[240:243], v[174:175], off
	global_load_dwordx4 v[244:247], v[174:175], off offset:256
	v_mov_b64_e32 v[174:175], v[172:173]
	s_waitcnt vmcnt(14)
	v_lshlrev_b32_e32 v212, 16, v146
	v_and_b32_e32 v213, 0xffff0000, v146
	v_lshlrev_b32_e32 v248, 16, v148
	v_and_b32_e32 v249, 0xffff0000, v148
	v_lshlrev_b32_e32 v146, 16, v147
	v_and_b32_e32 v147, 0xffff0000, v147
	v_lshlrev_b32_e32 v148, 16, v149
	v_and_b32_e32 v149, 0xffff0000, v149
	v_pk_fma_f32 v[142:143], v[142:143], v[134:135], v[212:213]
	v_pk_fma_f32 v[138:139], v[138:139], v[130:131], v[248:249]
	v_pk_fma_f32 v[144:145], v[144:145], v[136:137], v[146:147]
	v_pk_fma_f32 v[140:141], v[140:141], v[132:133], v[148:149]
	v_cvt_pk_bf16_f32 v146, v142, v143
	v_cvt_pk_bf16_f32 v147, v144, v145
	v_cvt_pk_bf16_f32 v148, v138, v139
	v_cvt_pk_bf16_f32 v149, v140, v141
	global_store_dwordx4 v[174:175], v[146:149], off
	v_lshlrev_b32_e32 v212, 16, v154
	v_and_b32_e32 v213, 0xffff0000, v154
	v_lshlrev_b32_e32 v248, 16, v156
	v_and_b32_e32 v249, 0xffff0000, v156
	v_lshlrev_b32_e32 v154, 16, v155
	v_and_b32_e32 v155, 0xffff0000, v155
	v_lshlrev_b32_e32 v156, 16, v157
	v_and_b32_e32 v157, 0xffff0000, v157
	v_pk_fma_f32 v[114:115], v[114:115], v[126:127], v[212:213]
	v_pk_fma_f32 v[110:111], v[110:111], v[122:123], v[248:249]
	v_pk_fma_f32 v[116:117], v[116:117], v[128:129], v[154:155]
	v_pk_fma_f32 v[112:113], v[112:113], v[124:125], v[156:157]
	v_cvt_pk_bf16_f32 v154, v114, v115
	v_cvt_pk_bf16_f32 v155, v116, v117
	v_cvt_pk_bf16_f32 v156, v110, v111
	v_cvt_pk_bf16_f32 v157, v112, v113
	global_store_dwordx4 v[174:175], v[154:157], off offset:256
	s_mov_b32 s20, 0x8000
	s_mov_b32 s21, 0
	v_lshl_add_u64 v[174:175], v[172:173], 0, s[20:21]
	s_waitcnt vmcnt(14)
	v_lshlrev_b32_e32 v212, 16, v180
	v_and_b32_e32 v213, 0xffff0000, v180
	v_lshlrev_b32_e32 v248, 16, v182
	v_and_b32_e32 v249, 0xffff0000, v182
	v_lshlrev_b32_e32 v180, 16, v181
	v_and_b32_e32 v181, 0xffff0000, v181
	v_lshlrev_b32_e32 v182, 16, v183
	v_and_b32_e32 v183, 0xffff0000, v183
	v_pk_fma_f32 v[118:119], v[118:119], v[134:135], v[212:213]
	v_pk_fma_f32 v[106:107], v[106:107], v[130:131], v[248:249]
	v_pk_fma_f32 v[120:121], v[120:121], v[136:137], v[180:181]
	v_pk_fma_f32 v[108:109], v[108:109], v[132:133], v[182:183]
	v_cvt_pk_bf16_f32 v180, v118, v119
	v_cvt_pk_bf16_f32 v181, v120, v121
	v_cvt_pk_bf16_f32 v182, v106, v107
	v_cvt_pk_bf16_f32 v183, v108, v109
	global_store_dwordx4 v[174:175], v[180:183], off
	v_lshlrev_b32_e32 v212, 16, v184
	v_and_b32_e32 v213, 0xffff0000, v184
	v_lshlrev_b32_e32 v248, 16, v186
	v_and_b32_e32 v249, 0xffff0000, v186
	v_lshlrev_b32_e32 v184, 16, v185
	v_and_b32_e32 v185, 0xffff0000, v185
	v_lshlrev_b32_e32 v186, 16, v187
	v_and_b32_e32 v187, 0xffff0000, v187
	v_pk_fma_f32 v[102:103], v[102:103], v[126:127], v[212:213]
	v_pk_fma_f32 v[94:95], v[94:95], v[122:123], v[248:249]
	v_pk_fma_f32 v[104:105], v[104:105], v[128:129], v[184:185]
	v_pk_fma_f32 v[96:97], v[96:97], v[124:125], v[186:187]
	v_cvt_pk_bf16_f32 v184, v102, v103
	v_cvt_pk_bf16_f32 v185, v104, v105
	v_cvt_pk_bf16_f32 v186, v94, v95
	v_cvt_pk_bf16_f32 v187, v96, v97
	global_store_dwordx4 v[174:175], v[184:187], off offset:256
	s_mov_b32 s20, 0x10000
	s_mov_b32 s21, 0
	v_lshl_add_u64 v[174:175], v[172:173], 0, s[20:21]
	s_waitcnt vmcnt(14)
	v_lshlrev_b32_e32 v212, 16, v188
	v_and_b32_e32 v213, 0xffff0000, v188
	v_lshlrev_b32_e32 v248, 16, v190
	v_and_b32_e32 v249, 0xffff0000, v190
	v_lshlrev_b32_e32 v188, 16, v189
	v_and_b32_e32 v189, 0xffff0000, v189
	v_lshlrev_b32_e32 v190, 16, v191
	v_and_b32_e32 v191, 0xffff0000, v191
	v_pk_fma_f32 v[98:99], v[98:99], v[134:135], v[212:213]
	v_pk_fma_f32 v[90:91], v[90:91], v[130:131], v[248:249]
	v_pk_fma_f32 v[100:101], v[100:101], v[136:137], v[188:189]
	v_pk_fma_f32 v[92:93], v[92:93], v[132:133], v[190:191]
	v_cvt_pk_bf16_f32 v188, v98, v99
	v_cvt_pk_bf16_f32 v189, v100, v101
	v_cvt_pk_bf16_f32 v190, v90, v91
	v_cvt_pk_bf16_f32 v191, v92, v93
	global_store_dwordx4 v[174:175], v[188:191], off
	v_lshlrev_b32_e32 v212, 16, v192
	v_and_b32_e32 v213, 0xffff0000, v192
	v_lshlrev_b32_e32 v248, 16, v194
	v_and_b32_e32 v249, 0xffff0000, v194
	v_lshlrev_b32_e32 v192, 16, v193
	v_and_b32_e32 v193, 0xffff0000, v193
	v_lshlrev_b32_e32 v194, 16, v195
	v_and_b32_e32 v195, 0xffff0000, v195
	v_pk_fma_f32 v[82:83], v[82:83], v[126:127], v[212:213]
	v_pk_fma_f32 v[78:79], v[78:79], v[122:123], v[248:249]
	v_pk_fma_f32 v[84:85], v[84:85], v[128:129], v[192:193]
	v_pk_fma_f32 v[80:81], v[80:81], v[124:125], v[194:195]
	v_cvt_pk_bf16_f32 v192, v82, v83
	v_cvt_pk_bf16_f32 v193, v84, v85
	v_cvt_pk_bf16_f32 v194, v78, v79
	v_cvt_pk_bf16_f32 v195, v80, v81
	global_store_dwordx4 v[174:175], v[192:195], off offset:256
	s_mov_b32 s20, 0x18000
	s_mov_b32 s21, 0
	v_lshl_add_u64 v[174:175], v[172:173], 0, s[20:21]
	s_waitcnt vmcnt(14)
	v_lshlrev_b32_e32 v212, 16, v196
	v_and_b32_e32 v213, 0xffff0000, v196
	v_lshlrev_b32_e32 v248, 16, v198
	v_and_b32_e32 v249, 0xffff0000, v198
	v_lshlrev_b32_e32 v196, 16, v197
	v_and_b32_e32 v197, 0xffff0000, v197
	v_lshlrev_b32_e32 v198, 16, v199
	v_and_b32_e32 v199, 0xffff0000, v199
	v_pk_fma_f32 v[86:87], v[86:87], v[134:135], v[212:213]
	v_pk_fma_f32 v[74:75], v[74:75], v[130:131], v[248:249]
	v_pk_fma_f32 v[88:89], v[88:89], v[136:137], v[196:197]
	v_pk_fma_f32 v[76:77], v[76:77], v[132:133], v[198:199]
	v_cvt_pk_bf16_f32 v196, v86, v87
	v_cvt_pk_bf16_f32 v197, v88, v89
	v_cvt_pk_bf16_f32 v198, v74, v75
	v_cvt_pk_bf16_f32 v199, v76, v77
	global_store_dwordx4 v[174:175], v[196:199], off
	v_lshlrev_b32_e32 v212, 16, v200
	v_and_b32_e32 v213, 0xffff0000, v200
	v_lshlrev_b32_e32 v248, 16, v202
	v_and_b32_e32 v249, 0xffff0000, v202
	v_lshlrev_b32_e32 v200, 16, v201
	v_and_b32_e32 v201, 0xffff0000, v201
	v_lshlrev_b32_e32 v202, 16, v203
	v_and_b32_e32 v203, 0xffff0000, v203
	v_pk_fma_f32 v[70:71], v[70:71], v[126:127], v[212:213]
	v_pk_fma_f32 v[66:67], v[66:67], v[122:123], v[248:249]
	v_pk_fma_f32 v[72:73], v[72:73], v[128:129], v[200:201]
	v_pk_fma_f32 v[68:69], v[68:69], v[124:125], v[202:203]
	v_cvt_pk_bf16_f32 v200, v70, v71
	v_cvt_pk_bf16_f32 v201, v72, v73
	v_cvt_pk_bf16_f32 v202, v66, v67
	v_cvt_pk_bf16_f32 v203, v68, v69
	global_store_dwordx4 v[174:175], v[200:203], off offset:256
	s_mov_b32 s20, 0x40000
	s_mov_b32 s21, 0
	v_lshl_add_u64 v[174:175], v[172:173], 0, s[20:21]
	s_waitcnt vmcnt(14)
	v_lshlrev_b32_e32 v212, 16, v204
	v_and_b32_e32 v213, 0xffff0000, v204
	v_lshlrev_b32_e32 v248, 16, v206
	v_and_b32_e32 v249, 0xffff0000, v206
	v_lshlrev_b32_e32 v204, 16, v205
	v_and_b32_e32 v205, 0xffff0000, v205
	v_lshlrev_b32_e32 v206, 16, v207
	v_and_b32_e32 v207, 0xffff0000, v207
	v_pk_fma_f32 v[62:63], v[62:63], v[134:135], v[212:213]
	v_pk_fma_f32 v[58:59], v[58:59], v[130:131], v[248:249]
	v_pk_fma_f32 v[64:65], v[64:65], v[136:137], v[204:205]
	v_pk_fma_f32 v[60:61], v[60:61], v[132:133], v[206:207]
	v_cvt_pk_bf16_f32 v204, v62, v63
	v_cvt_pk_bf16_f32 v205, v64, v65
	v_cvt_pk_bf16_f32 v206, v58, v59
	v_cvt_pk_bf16_f32 v207, v60, v61
	global_store_dwordx4 v[174:175], v[204:207], off
	v_lshlrev_b32_e32 v212, 16, v208
	v_and_b32_e32 v213, 0xffff0000, v208
	v_lshlrev_b32_e32 v248, 16, v210
	v_and_b32_e32 v249, 0xffff0000, v210
	v_lshlrev_b32_e32 v208, 16, v209
	v_and_b32_e32 v209, 0xffff0000, v209
	v_lshlrev_b32_e32 v210, 16, v211
	v_and_b32_e32 v211, 0xffff0000, v211
	v_pk_fma_f32 v[50:51], v[50:51], v[126:127], v[212:213]
	v_pk_fma_f32 v[46:47], v[46:47], v[122:123], v[248:249]
	v_pk_fma_f32 v[52:53], v[52:53], v[128:129], v[208:209]
	v_pk_fma_f32 v[48:49], v[48:49], v[124:125], v[210:211]
	v_cvt_pk_bf16_f32 v208, v50, v51
	v_cvt_pk_bf16_f32 v209, v52, v53
	v_cvt_pk_bf16_f32 v210, v46, v47
	v_cvt_pk_bf16_f32 v211, v48, v49
	global_store_dwordx4 v[174:175], v[208:211], off offset:256
	s_mov_b32 s20, 0x48000
	s_mov_b32 s21, 0
	v_lshl_add_u64 v[174:175], v[172:173], 0, s[20:21]
	s_waitcnt vmcnt(14)
	v_lshlrev_b32_e32 v212, 16, v222
	v_and_b32_e32 v213, 0xffff0000, v222
	v_lshlrev_b32_e32 v248, 16, v224
	v_and_b32_e32 v249, 0xffff0000, v224
	v_lshlrev_b32_e32 v222, 16, v223
	v_and_b32_e32 v223, 0xffff0000, v223
	v_lshlrev_b32_e32 v224, 16, v225
	v_and_b32_e32 v225, 0xffff0000, v225
	v_pk_fma_f32 v[54:55], v[54:55], v[134:135], v[212:213]
	v_pk_fma_f32 v[42:43], v[42:43], v[130:131], v[248:249]
	v_pk_fma_f32 v[56:57], v[56:57], v[136:137], v[222:223]
	v_pk_fma_f32 v[44:45], v[44:45], v[132:133], v[224:225]
	v_cvt_pk_bf16_f32 v222, v54, v55
	v_cvt_pk_bf16_f32 v223, v56, v57
	v_cvt_pk_bf16_f32 v224, v42, v43
	v_cvt_pk_bf16_f32 v225, v44, v45
	global_store_dwordx4 v[174:175], v[222:225], off
	v_lshlrev_b32_e32 v212, 16, v226
	v_and_b32_e32 v213, 0xffff0000, v226
	v_lshlrev_b32_e32 v248, 16, v228
	v_and_b32_e32 v249, 0xffff0000, v228
	v_lshlrev_b32_e32 v226, 16, v227
	v_and_b32_e32 v227, 0xffff0000, v227
	v_lshlrev_b32_e32 v228, 16, v229
	v_and_b32_e32 v229, 0xffff0000, v229
	v_pk_fma_f32 v[38:39], v[38:39], v[126:127], v[212:213]
	v_pk_fma_f32 v[30:31], v[30:31], v[122:123], v[248:249]
	v_pk_fma_f32 v[40:41], v[40:41], v[128:129], v[226:227]
	v_pk_fma_f32 v[32:33], v[32:33], v[124:125], v[228:229]
	v_cvt_pk_bf16_f32 v226, v38, v39
	v_cvt_pk_bf16_f32 v227, v40, v41
	v_cvt_pk_bf16_f32 v228, v30, v31
	v_cvt_pk_bf16_f32 v229, v32, v33
	global_store_dwordx4 v[174:175], v[226:229], off offset:256
	s_mov_b32 s20, 0x50000
	s_mov_b32 s21, 0
	v_lshl_add_u64 v[174:175], v[172:173], 0, s[20:21]
	s_waitcnt vmcnt(14)
	v_lshlrev_b32_e32 v212, 16, v230
	v_and_b32_e32 v213, 0xffff0000, v230
	v_lshlrev_b32_e32 v248, 16, v232
	v_and_b32_e32 v249, 0xffff0000, v232
	v_lshlrev_b32_e32 v230, 16, v231
	v_and_b32_e32 v231, 0xffff0000, v231
	v_lshlrev_b32_e32 v232, 16, v233
	v_and_b32_e32 v233, 0xffff0000, v233
	v_pk_fma_f32 v[34:35], v[34:35], v[134:135], v[212:213]
	v_pk_fma_f32 v[26:27], v[26:27], v[130:131], v[248:249]
	v_pk_fma_f32 v[36:37], v[36:37], v[136:137], v[230:231]
	v_pk_fma_f32 v[28:29], v[28:29], v[132:133], v[232:233]
	v_cvt_pk_bf16_f32 v230, v34, v35
	v_cvt_pk_bf16_f32 v231, v36, v37
	v_cvt_pk_bf16_f32 v232, v26, v27
	v_cvt_pk_bf16_f32 v233, v28, v29
	global_store_dwordx4 v[174:175], v[230:233], off
	v_lshlrev_b32_e32 v212, 16, v234
	v_and_b32_e32 v213, 0xffff0000, v234
	v_lshlrev_b32_e32 v248, 16, v236
	v_and_b32_e32 v249, 0xffff0000, v236
	v_lshlrev_b32_e32 v234, 16, v235
	v_and_b32_e32 v235, 0xffff0000, v235
	v_lshlrev_b32_e32 v236, 16, v237
	v_and_b32_e32 v237, 0xffff0000, v237
	v_pk_fma_f32 v[18:19], v[18:19], v[126:127], v[212:213]
	v_pk_fma_f32 v[14:15], v[14:15], v[122:123], v[248:249]
	v_pk_fma_f32 v[20:21], v[20:21], v[128:129], v[234:235]
	v_pk_fma_f32 v[16:17], v[16:17], v[124:125], v[236:237]
	v_cvt_pk_bf16_f32 v234, v18, v19
	v_cvt_pk_bf16_f32 v235, v20, v21
	v_cvt_pk_bf16_f32 v236, v14, v15
	v_cvt_pk_bf16_f32 v237, v16, v17
	global_store_dwordx4 v[174:175], v[234:237], off offset:256
	s_mov_b32 s20, 0x58000
	s_mov_b32 s21, 0
	v_lshl_add_u64 v[174:175], v[172:173], 0, s[20:21]
	s_waitcnt vmcnt(14)
	v_lshlrev_b32_e32 v212, 16, v240
	v_and_b32_e32 v213, 0xffff0000, v240
	v_lshlrev_b32_e32 v248, 16, v242
	v_and_b32_e32 v249, 0xffff0000, v242
	v_lshlrev_b32_e32 v240, 16, v241
	v_and_b32_e32 v241, 0xffff0000, v241
	v_lshlrev_b32_e32 v242, 16, v243
	v_and_b32_e32 v243, 0xffff0000, v243
	v_pk_fma_f32 v[22:23], v[22:23], v[134:135], v[212:213]
	v_pk_fma_f32 v[10:11], v[10:11], v[130:131], v[248:249]
	v_pk_fma_f32 v[24:25], v[24:25], v[136:137], v[240:241]
	v_pk_fma_f32 v[12:13], v[12:13], v[132:133], v[242:243]
	v_cvt_pk_bf16_f32 v240, v22, v23
	v_cvt_pk_bf16_f32 v241, v24, v25
	v_cvt_pk_bf16_f32 v242, v10, v11
	v_cvt_pk_bf16_f32 v243, v12, v13
	global_store_dwordx4 v[174:175], v[240:243], off
	v_lshlrev_b32_e32 v212, 16, v244
	v_and_b32_e32 v213, 0xffff0000, v244
	v_lshlrev_b32_e32 v248, 16, v246
	v_and_b32_e32 v249, 0xffff0000, v246
	v_lshlrev_b32_e32 v244, 16, v245
	v_and_b32_e32 v245, 0xffff0000, v245
	v_lshlrev_b32_e32 v246, 16, v247
	v_and_b32_e32 v247, 0xffff0000, v247
	v_pk_fma_f32 v[6:7], v[6:7], v[126:127], v[212:213]
	v_pk_fma_f32 v[2:3], v[2:3], v[122:123], v[248:249]
	v_pk_fma_f32 v[8:9], v[8:9], v[128:129], v[244:245]
	v_pk_fma_f32 v[4:5], v[4:5], v[124:125], v[246:247]
	v_cvt_pk_bf16_f32 v244, v6, v7
	v_cvt_pk_bf16_f32 v245, v8, v9
	v_cvt_pk_bf16_f32 v246, v2, v3
	v_cvt_pk_bf16_f32 v247, v4, v5
	global_store_dwordx4 v[174:175], v[244:247], off offset:256
	s_andn2_b64 vcc, exec, s[0:1]
	s_mov_b64 s[0:1], -1
	s_movk_i32 s60, 0xe400
	s_mov_b32 s98, 1
	s_cbranch_vccnz .LBB0_373
	s_andn2_b64 vcc, exec, s[4:5]
	s_cbranch_vccnz .LBB0_372
	s_barrier
	s_branch .LBB0_372
.Lrelax_g5_w1:
	s_waitcnt vmcnt(24)
	s_branch .Lback_g5_w1
.Lrelax_g5_w2:
	s_waitcnt vmcnt(24)
	s_branch .Lback_g5_w2
